# v6
# speedup vs baseline: 1.0147x; 1.0147x over previous
.LBB0_54:
	v_exp_f32_e32 v238, v80
	v_exp_f32_e32 v240, v81
	v_exp_f32_e32 v241, v82
	v_exp_f32_e32 v243, v83
	v_exp_f32_e32 v244, v84
	v_exp_f32_e32 v133, v64
	v_exp_f32_e32 v132, v66
	v_add_f32_e32 v64, 0, v238
	v_add_f32_e32 v66, 0, v148
	v_exp_f32_e32 v245, v85
	v_add_f32_e32 v64, v240, v64
	v_add_f32_e32 v66, v149, v66
	v_exp_f32_e32 v239, v86
	v_add_f32_e32 v64, v241, v64
	v_add_f32_e32 v66, v150, v66
	v_exp_f32_e32 v242, v87
	v_add_f32_e32 v64, v243, v64
	v_add_f32_e32 v66, v151, v66
	v_exp_f32_e32 v234, v88
	v_add_f32_e32 v64, v244, v64
	v_add_f32_e32 v66, v155, v66
	v_exp_f32_e32 v235, v89
	v_add_f32_e32 v64, v245, v64
	v_add_f32_e32 v66, v168, v66
	v_exp_f32_e32 v236, v90
	v_add_f32_e32 v64, v239, v64
	v_add_f32_e32 v66, v169, v66
	v_exp_f32_e32 v237, v91
	v_add_f32_e32 v64, v242, v64
	v_add_f32_e32 v66, v170, v66
	v_exp_f32_e32 v230, v92
	v_add_f32_e32 v64, v234, v64
	v_add_f32_e32 v66, v171, v66
	v_exp_f32_e32 v232, v93
	v_add_f32_e32 v64, v235, v64
	v_add_f32_e32 v66, v191, v66
	v_exp_f32_e32 v231, v94
	v_add_f32_e32 v64, v236, v64
	v_add_f32_e32 v66, v192, v66
	v_exp_f32_e32 v233, v95
	v_add_f32_e32 v64, v237, v64
	v_add_f32_e32 v66, v195, v66
	v_add_f32_e32 v64, v230, v64
	v_add_f32_e32 v66, v196, v66
	v_exp_f32_e32 v226, v65
	v_add_f32_e32 v64, v232, v64
	v_add_f32_e32 v66, v197, v66
	v_add_f32_e32 v64, v231, v64
	v_add_f32_e32 v66, v198, v66
	v_exp_f32_e32 v134, v67
	v_add_f32_e32 v64, v233, v64
	v_add_f32_e32 v66, v199, v66
	v_exp_f32_e32 v135, v68
	v_add_f32_e32 v64, v133, v64
	v_add_f32_e32 v66, v200, v66
	v_exp_f32_e32 v227, v69
	v_add_f32_e32 v64, v226, v64
	v_add_f32_e32 v66, v201, v66
	v_mad_i64_i32 v[156:157], s[8:9], v139, s73, 0
	v_mad_i64_i32 v[158:159], s[8:9], v140, s73, 0
	v_mad_i64_i32 v[160:161], s[8:9], v141, s73, 0
	v_mad_i64_i32 v[162:163], s[8:9], v142, s73, 0
	v_mad_i64_i32 v[164:165], s[8:9], v143, s73, 0
	v_mad_i64_i32 v[166:167], s[8:9], v144, s73, 0
	v_exp_f32_e32 v228, v70
	v_add_f32_e32 v64, v132, v64
	v_add_f32_e32 v66, v211, v66
	v_exp_f32_e32 v229, v71
	v_add_f32_e32 v64, v134, v64
	v_add_f32_e32 v66, v212, v66
	v_readlane_b32 s8, v255, 9
	v_exp_f32_e32 v124, v72
	v_add_f32_e32 v64, v135, v64
	v_add_f32_e32 v66, v213, v66
	s_add_u32 s46, s8, s10
	v_readlane_b32 s8, v255, 10
	v_exp_f32_e32 v125, v73
	v_add_f32_e32 v64, v227, v64
	v_add_f32_e32 v66, v214, v66
	s_addc_u32 s47, s8, s11
	v_exp_f32_e32 v126, v74
	v_add_f32_e32 v64, v228, v64
	v_add_f32_e32 v66, v215, v66
	s_add_u32 s20, s78, s10
	v_exp_f32_e32 v127, v75
	v_add_f32_e32 v64, v229, v64
	v_add_f32_e32 v66, v216, v66
	s_addc_u32 s21, s79, s11
	v_exp_f32_e32 v128, v76
	v_add_f32_e32 v64, v124, v64
	v_add_f32_e32 v66, v217, v66
	s_cmp_lg_u32 0, -1
	v_exp_f32_e32 v129, v77
	v_add_f32_e32 v64, v125, v64
	v_add_f32_e32 v66, v218, v66
	s_cselect_b32 s8, 0, 0
	v_exp_f32_e32 v130, v78
	v_add_f32_e32 v64, v126, v64
	v_add_f32_e32 v66, v219, v66
	s_addk_i32 s8, 0x4000
	v_exp_f32_e32 v131, v79
	v_add_f32_e32 v64, v127, v64
	v_add_f32_e32 v66, v220, v66
	s_add_u32 s10, s23, s10
	v_add_f32_e32 v64, v128, v64
	v_add_f32_e32 v66, v221, v66
	s_addc_u32 s11, s22, s11
	v_add_f32_e32 v64, v129, v64
	v_add_f32_e32 v66, v222, v66
	s_add_u32 s77, s18, s10
	v_add_f32_e32 v64, v130, v64
	v_add_f32_e32 v66, v223, v66
	s_addc_u32 s66, s19, s11
	s_lshr_b32 s10, s27, 7
	v_add_f32_e32 v194, v131, v64
	v_bfe_u32 v64, v138, 4, 4
	v_bfe_u32 v65, v138, 3, 4
	v_add_f32_e32 v66, v224, v66
	s_mul_i32 s10, s10, 0xc0000
	v_add_f32_e32 v192, 0, v66
	s_mov_b32 s25, 1
	v_add_u32_e32 v195, s8, v172
	v_cmp_gt_u32_e64 s[8:9], 32, v137
	v_lshl_add_u32 v191, v136, 2, s59
	v_mul_u32_u24_e32 v168, 0x1800, v64
	v_mov_b32_e32 v169, v181
	v_mul_u32_u24_e32 v170, 0x1800, v65
	v_mov_b32_e32 v171, v181
	s_add_u32 s67, s10, 0xffe80000
	s_add_u32 s88, s10, 0xfff40000
	s_mov_b64 s[22:23], 0
	s_waitcnt lgkmcnt(0)
	s_barrier
	v_fma_f32 v192, v192, v193, v194
	v_cvt_pk_bf16_f32 v250, v238, v240
	v_cvt_pk_bf16_f32 v251, v241, v243
	v_cvt_pk_bf16_f32 v252, v244, v245
	v_cvt_pk_bf16_f32 v253, v239, v242
	v_cvt_pk_bf16_f32 v238, v234, v235
	v_cvt_pk_bf16_f32 v239, v236, v237
	v_cvt_pk_bf16_f32 v240, v230, v232
	v_cvt_pk_bf16_f32 v241, v231, v233
	v_cvt_pk_bf16_f32 v242, v133, v226
	v_cvt_pk_bf16_f32 v243, v132, v134
	v_cvt_pk_bf16_f32 v244, v135, v227
	v_cvt_pk_bf16_f32 v245, v228, v229
	v_cvt_pk_bf16_f32 v246, v124, v125
	v_cvt_pk_bf16_f32 v247, v126, v127
	v_cvt_pk_bf16_f32 v248, v128, v129
	v_cvt_pk_bf16_f32 v249, v130, v131
	s_nop 1
	v_permlane32_swap_b32_e32 v250, v252
	v_permlane32_swap_b32_e32 v251, v253
	v_permlane32_swap_b32_e32 v238, v240
	v_permlane32_swap_b32_e32 v239, v241
	v_permlane32_swap_b32_e32 v242, v244
	v_permlane32_swap_b32_e32 v243, v245
	v_permlane32_swap_b32_e32 v246, v248
	v_permlane32_swap_b32_e32 v247, v249
	v_mov_b32_e32 v234, v250
	v_mov_b32_e32 v235, v251
	v_mov_b32_e32 v236, v252
	v_mov_b32_e32 v237, v253
	v_xor_b32_e32 v196, 0x80000000, v190
	v_mov_b32_e32 v197, v196
	v_mov_b32_e32 v198, v196
	v_mov_b32_e32 v199, v196
	v_mov_b32_e32 v200, v196
	v_mov_b32_e32 v201, v196
	v_mov_b32_e32 v202, v196
	v_mov_b32_e32 v203, v196
	v_mov_b32_e32 v204, v196
	v_mov_b32_e32 v205, v196
	v_mov_b32_e32 v206, v196
	v_mov_b32_e32 v207, v196
	v_mov_b32_e32 v208, v196
	v_mov_b32_e32 v209, v196
	v_mov_b32_e32 v210, v196
	v_mov_b32_e32 v211, v196
	v_mov_b32_e32 v253, 1.0
	v_add_u32_e32 v156, v156, v180
	v_add_u32_e32 v158, v158, v180
	v_add_u32_e32 v160, v160, v154
	v_add_u32_e32 v162, v162, v154
	v_add_u32_e32 v164, v164, v180
	v_add_u32_e32 v166, v166, v180
	v_add_u32_e32 v168, v168, v180
	v_add_u32_e32 v170, v170, v154
.LBB0_55:
	s_and_b32 s89, s25, 1
	s_lshl_b32 s10, s89, 14
	s_add_i32 s10, s10, 0x10000
	v_add_u32_e32 v193, s10, v182
	v_add_u32_e32 v194, s10, v186
	v_add_u32_e32 v232, s10, v187
	v_add_u32_e32 v233, s10, v188
	s_xor_b32 s11, s89, 1
	s_lshl_b32 s11, s11, 15
	v_add_u32_e32 v189, s11, v195
	ds_read_b128 v[228:231], v193
	ds_read_b128 v[224:227], v193 offset:4096
	s_waitcnt lgkmcnt(1)
	v_mfma_f32_32x32x16_bf16 v[80:95], v[228:231], v[108:111], v[196:211]
	ds_read_b128 v[228:231], v194
	s_waitcnt lgkmcnt(1)
	v_mfma_f32_32x32x16_bf16 v[64:79], v[224:227], v[108:111], v[196:211]
	ds_read_b128 v[224:227], v194 offset:4096
	s_waitcnt lgkmcnt(1)
	v_mfma_f32_32x32x16_bf16 v[80:95], v[228:231], v[104:107], v[80:95]
	ds_read_b128 v[228:231], v232
	s_waitcnt lgkmcnt(1)
	v_mfma_f32_32x32x16_bf16 v[64:79], v[224:227], v[104:107], v[64:79]
	ds_read_b128 v[224:227], v232 offset:4096
	s_waitcnt lgkmcnt(1)
	v_mfma_f32_32x32x16_bf16 v[80:95], v[228:231], v[100:103], v[80:95]
	ds_read_b128 v[228:231], v233
	s_waitcnt lgkmcnt(1)
	v_mfma_f32_32x32x16_bf16 v[64:79], v[224:227], v[100:103], v[64:79]
	ds_read_b128 v[224:227], v233 offset:4096
	ds_read_b64_tr_b16 v[212:213], v189 offset:0
	ds_read_b64_tr_b16 v[214:215], v189 offset:0x800
	ds_read_b64_tr_b16 v[216:217], v189 offset:0x1000
	ds_read_b64_tr_b16 v[218:219], v189 offset:0x1800
	ds_read_b64_tr_b16 v[220:221], v189 offset:0x2000
	ds_read_b64_tr_b16 v[222:223], v189 offset:0x2800
	s_waitcnt lgkmcnt(7)
	v_mfma_f32_32x32x16_bf16 v[80:95], v[228:231], v[96:99], v[80:95]
	s_waitcnt lgkmcnt(6)
	v_mfma_f32_32x32x16_bf16 v[64:79], v[224:227], v[96:99], v[64:79]
	ds_read_b64_tr_b16 v[224:225], v189 offset:0x3000
	ds_read_b64_tr_b16 v[226:227], v189 offset:0x3800
	s_cmp_eq_u32 s67, s22
	s_cbranch_scc1 .Lda1_sl_last
	s_add_u32 s10, s77, s22
	s_addc_u32 s11, s66, s23
	s_add_u32 s48, s10, 0x126c3400
	s_addc_u32 s49, s11, 0
	s_add_u32 s50, s77, s22
	s_addc_u32 s51, s66, s23
	s_add_u32 s50, s50, 0x126c2c00
	s_addc_u32 s51, s51, 0
	global_load_dwordx4 v[128:131], v156, s[48:49]
	global_load_dwordx4 v[124:127], v158, s[48:49]
	global_load_dwordx4 v[132:135], v160, s[50:51]
	global_load_dwordx4 v[112:115], v166, s[48:49]
	global_load_dwordx4 v[116:119], v164, s[48:49]
	global_load_dwordx4 v[120:123], v162, s[50:51]
	s_branch .LBB0_61
.Lda1_sl_last:
	global_load_dwordx4 v[128:131], v168, s[20:21]
	global_load_dwordx4 v[124:127], v168, s[20:21]
	global_load_dwordx4 v[132:135], v170, s[46:47]
.LBB0_61:
	s_xor_b32 s48, s89, 1
	s_lshl_b32 s49, s48, 15
	s_waitcnt lgkmcnt(4)
	v_mfma_f32_32x32x16_bf16 v[0:15], v[234:237], v[212:215], v[0:15]
	ds_read_b64_tr_b16 v[212:213], v189 offset:0x200
	ds_read_b64_tr_b16 v[214:215], v189 offset:0xa00
	v_mfma_f32_32x32x16_bf16 v[0:15], v[238:241], v[216:219], v[0:15]
	ds_read_b64_tr_b16 v[216:217], v189 offset:0x1200
	ds_read_b64_tr_b16 v[218:219], v189 offset:0x1a00
	v_max3_f32 v250, v80, v81, v82
	v_max3_f32 v250, v250, v83, v84
	v_max3_f32 v250, v250, v85, v86
	v_max3_f32 v250, v250, v87, v88
	v_max3_f32 v250, v250, v89, v90
	v_max3_f32 v250, v250, v91, v92
	s_waitcnt lgkmcnt(4)
	v_mfma_f32_32x32x16_bf16 v[0:15], v[242:245], v[220:223], v[0:15]
	ds_read_b64_tr_b16 v[220:221], v189 offset:0x2200
	ds_read_b64_tr_b16 v[222:223], v189 offset:0x2a00
	v_max3_f32 v250, v250, v93, v94
	v_max3_f32 v250, v250, v95, v64
	v_max3_f32 v250, v250, v65, v66
	v_max3_f32 v250, v250, v67, v68
	v_max3_f32 v250, v250, v69, v70
	v_max3_f32 v250, v250, v71, v72
	v_mfma_f32_32x32x16_bf16 v[0:15], v[246:249], v[224:227], v[0:15]
	ds_read_b64_tr_b16 v[224:225], v189 offset:0x3200
	ds_read_b64_tr_b16 v[226:227], v189 offset:0x3a00
	v_max3_f32 v250, v250, v73, v74
	v_max3_f32 v250, v250, v75, v76
	v_max3_f32 v250, v250, v77, v78
	v_max_f32_e32 v250, v250, v79
	v_mov_b32_e32 v251, v250
	s_waitcnt lgkmcnt(4)
	v_mfma_f32_32x32x16_bf16 v[16:31], v[234:237], v[212:215], v[16:31]
	ds_read_b64_tr_b16 v[212:213], v189 offset:0x400
	ds_read_b64_tr_b16 v[214:215], v189 offset:0xc00
	v_permlane32_swap_b32_e32 v250, v251
	v_max_f32_e32 v251, v250, v251
	v_cmp_ge_f32_e32 vcc, s63, v251
	s_cmp_eq_u64 vcc, exec
	s_cbranch_scc0 .Lda1_rare1
.Lda1_cont1:
	v_mfma_f32_32x32x16_bf16 v[16:31], v[238:241], v[216:219], v[16:31]
	ds_read_b64_tr_b16 v[216:217], v189 offset:0x1400
	ds_read_b64_tr_b16 v[218:219], v189 offset:0x1c00
	v_exp_f32_e32 v80, v80
	v_exp_f32_e32 v81, v81
	v_add_f32_e32 v252, 0, v80
	v_exp_f32_e32 v82, v82
	v_add_f32_e32 v252, v81, v252
	v_exp_f32_e32 v83, v83
	v_add_f32_e32 v252, v82, v252
	s_waitcnt lgkmcnt(4)
	v_mfma_f32_32x32x16_bf16 v[16:31], v[242:245], v[220:223], v[16:31]
	ds_read_b64_tr_b16 v[220:221], v189 offset:0x2400
	ds_read_b64_tr_b16 v[222:223], v189 offset:0x2c00
	v_cvt_pk_bf16_f32 v136, v80, v81
	v_exp_f32_e32 v84, v84
	v_add_f32_e32 v252, v83, v252
	v_exp_f32_e32 v85, v85
	v_add_f32_e32 v252, v84, v252
	v_cvt_pk_bf16_f32 v137, v82, v83
	v_exp_f32_e32 v86, v86
	v_add_f32_e32 v252, v85, v252
	v_mfma_f32_32x32x16_bf16 v[16:31], v[246:249], v[224:227], v[16:31]
	ds_read_b64_tr_b16 v[224:225], v189 offset:0x3400
	ds_read_b64_tr_b16 v[226:227], v189 offset:0x3c00
	v_exp_f32_e32 v87, v87
	v_add_f32_e32 v252, v86, v252
	v_cvt_pk_bf16_f32 v138, v84, v85
	v_exp_f32_e32 v88, v88
	v_add_f32_e32 v252, v87, v252
	v_exp_f32_e32 v89, v89
	v_add_f32_e32 v252, v88, v252
	v_cvt_pk_bf16_f32 v139, v86, v87
	s_waitcnt lgkmcnt(4)
	v_mfma_f32_32x32x16_bf16 v[32:47], v[234:237], v[212:215], v[32:47]
	ds_read_b64_tr_b16 v[212:213], v189 offset:0x600
	ds_read_b64_tr_b16 v[214:215], v189 offset:0xe00
	v_exp_f32_e32 v90, v90
	v_add_f32_e32 v252, v89, v252
	v_exp_f32_e32 v91, v91
	v_permlane32_swap_b32_e32 v136, v138
	v_permlane32_swap_b32_e32 v137, v139
	v_add_f32_e32 v252, v90, v252
	v_cvt_pk_bf16_f32 v140, v88, v89
	v_exp_f32_e32 v92, v92
	v_mfma_f32_32x32x16_bf16 v[32:47], v[238:241], v[216:219], v[32:47]
	ds_read_b64_tr_b16 v[216:217], v189 offset:0x1600
	ds_read_b64_tr_b16 v[218:219], v189 offset:0x1e00
	v_add_f32_e32 v252, v91, v252
	v_exp_f32_e32 v93, v93
	v_add_f32_e32 v252, v92, v252
	v_cvt_pk_bf16_f32 v141, v90, v91
	v_exp_f32_e32 v94, v94
	v_add_f32_e32 v252, v93, v252
	v_exp_f32_e32 v95, v95
	v_add_f32_e32 v252, v94, v252
	s_waitcnt lgkmcnt(4)
	v_mfma_f32_32x32x16_bf16 v[32:47], v[242:245], v[220:223], v[32:47]
	ds_read_b64_tr_b16 v[220:221], v189 offset:0x2600
	ds_read_b64_tr_b16 v[222:223], v189 offset:0x2e00
	v_cvt_pk_bf16_f32 v142, v92, v93
	v_exp_f32_e32 v64, v64
	v_add_f32_e32 v252, v95, v252
	v_exp_f32_e32 v65, v65
	v_add_f32_e32 v252, v64, v252
	v_cvt_pk_bf16_f32 v143, v94, v95
	v_exp_f32_e32 v66, v66
	v_add_f32_e32 v252, v65, v252
	v_mfma_f32_32x32x16_bf16 v[32:47], v[246:249], v[224:227], v[32:47]
	ds_read_b64_tr_b16 v[224:225], v189 offset:0x3600
	ds_read_b64_tr_b16 v[226:227], v189 offset:0x3e00
	v_exp_f32_e32 v67, v67
	v_permlane32_swap_b32_e32 v140, v142
	v_permlane32_swap_b32_e32 v141, v143
	v_add_f32_e32 v252, v66, v252
	v_cvt_pk_bf16_f32 v144, v64, v65
	v_exp_f32_e32 v68, v68
	v_add_f32_e32 v252, v67, v252
	v_exp_f32_e32 v69, v69
	s_waitcnt lgkmcnt(4)
	v_mfma_f32_32x32x16_bf16 v[48:63], v[234:237], v[212:215], v[48:63]
	v_add_f32_e32 v252, v68, v252
	v_cvt_pk_bf16_f32 v145, v66, v67
	v_exp_f32_e32 v70, v70
	v_add_f32_e32 v252, v69, v252
	v_exp_f32_e32 v71, v71
	v_add_f32_e32 v252, v70, v252
	v_cvt_pk_bf16_f32 v146, v68, v69
	v_exp_f32_e32 v72, v72
	v_mfma_f32_32x32x16_bf16 v[48:63], v[238:241], v[216:219], v[48:63]
	v_add_f32_e32 v252, v71, v252
	v_exp_f32_e32 v73, v73
	v_add_f32_e32 v252, v72, v252
	v_cvt_pk_bf16_f32 v147, v70, v71
	v_exp_f32_e32 v74, v74
	v_add_f32_e32 v252, v73, v252
	v_exp_f32_e32 v75, v75
	v_permlane32_swap_b32_e32 v144, v146
	s_waitcnt lgkmcnt(0)
	v_mfma_f32_32x32x16_bf16 v[48:63], v[242:245], v[220:223], v[48:63]
	v_permlane32_swap_b32_e32 v145, v147
	v_add_f32_e32 v252, v74, v252
	v_cvt_pk_bf16_f32 v148, v72, v73
	v_exp_f32_e32 v76, v76
	v_add_f32_e32 v252, v75, v252
	v_exp_f32_e32 v77, v77
	v_add_f32_e32 v252, v76, v252
	v_cvt_pk_bf16_f32 v149, v74, v75
	v_exp_f32_e32 v78, v78
	v_mfma_f32_32x32x16_bf16 v[48:63], v[246:249], v[224:227], v[48:63]
	ds_read_b128 v[228:231], v193 offset:8192
	ds_read_b128 v[224:227], v193 offset:12288
	v_add_f32_e32 v252, v77, v252
	v_exp_f32_e32 v79, v79
	v_add_f32_e32 v252, v78, v252
	v_cvt_pk_bf16_f32 v150, v76, v77
	v_add_f32_e32 v252, v79, v252
	v_cvt_pk_bf16_f32 v151, v78, v79
	v_fma_f32 v192, v192, v253, v252
	s_nop 0
	s_nop 0
	v_permlane32_swap_b32_e32 v148, v150
	v_permlane32_swap_b32_e32 v149, v151
.LBB0_62:
	v_cmp_gt_f32_e32 vcc, 1.0, v253
	s_barrier
	s_cbranch_vccz .LBB0_66
	s_and_saveexec_b64 s[10:11], s[8:9]
	ds_write_b32 v191, v253 offset:128
	s_or_b64 exec, exec, s[10:11]
	s_waitcnt lgkmcnt(0)
	v_add_u32_e32 v251, s59, v152
	ds_read_b128 v[212:215], v251 offset:224
	ds_read_b128 v[216:219], v251 offset:192
	ds_read_b128 v[220:223], v251 offset:160
	ds_read_b128 v[224:227], v251 offset:128
	s_waitcnt lgkmcnt(3)
	v_pk_mul_f32 v[12:13], v[12:13], v[212:213]
	s_waitcnt lgkmcnt(2)
	v_pk_mul_f32 v[8:9], v[8:9], v[216:217]
	s_waitcnt lgkmcnt(1)
	v_pk_mul_f32 v[4:5], v[4:5], v[220:221]
	v_pk_mul_f32 v[14:15], v[14:15], v[214:215]
	v_pk_mul_f32 v[10:11], v[10:11], v[218:219]
	v_pk_mul_f32 v[6:7], v[6:7], v[222:223]
	s_waitcnt lgkmcnt(0)
	v_pk_mul_f32 v[2:3], v[2:3], v[226:227]
	v_pk_mul_f32 v[0:1], v[0:1], v[224:225]
	v_pk_mul_f32 v[28:29], v[28:29], v[212:213]
	v_pk_mul_f32 v[24:25], v[24:25], v[216:217]
	v_pk_mul_f32 v[20:21], v[20:21], v[220:221]
	v_pk_mul_f32 v[30:31], v[30:31], v[214:215]
	v_pk_mul_f32 v[26:27], v[26:27], v[218:219]
	v_pk_mul_f32 v[22:23], v[22:23], v[222:223]
	v_pk_mul_f32 v[18:19], v[18:19], v[226:227]
	v_pk_mul_f32 v[16:17], v[16:17], v[224:225]
	v_pk_mul_f32 v[44:45], v[44:45], v[212:213]
	v_pk_mul_f32 v[40:41], v[40:41], v[216:217]
	v_pk_mul_f32 v[36:37], v[36:37], v[220:221]
	v_pk_mul_f32 v[46:47], v[46:47], v[214:215]
	v_pk_mul_f32 v[42:43], v[42:43], v[218:219]
	v_pk_mul_f32 v[38:39], v[38:39], v[222:223]
	v_pk_mul_f32 v[34:35], v[34:35], v[226:227]
	v_pk_mul_f32 v[32:33], v[32:33], v[224:225]
	v_pk_mul_f32 v[60:61], v[60:61], v[212:213]
	v_pk_mul_f32 v[56:57], v[56:57], v[216:217]
	v_pk_mul_f32 v[52:53], v[52:53], v[220:221]
	v_pk_mul_f32 v[62:63], v[62:63], v[214:215]
	v_pk_mul_f32 v[58:59], v[58:59], v[218:219]
	v_pk_mul_f32 v[54:55], v[54:55], v[222:223]
	v_pk_mul_f32 v[50:51], v[50:51], v[226:227]
	v_pk_mul_f32 v[48:49], v[48:49], v[224:225]
	v_mov_b32_e32 v253, 1.0
	ds_read_b128 v[228:231], v193 offset:8192
	ds_read_b128 v[224:227], v193 offset:12288
.LBB0_66:
	v_lshl_add_u32 v189, s89, 15, v153
	s_waitcnt lgkmcnt(1)
	v_mfma_f32_32x32x16_bf16 v[80:95], v[228:231], v[108:111], v[196:211]
	ds_read_b128 v[228:231], v194 offset:8192
	s_waitcnt lgkmcnt(1)
	v_mfma_f32_32x32x16_bf16 v[64:79], v[224:227], v[108:111], v[196:211]
	ds_read_b128 v[224:227], v194 offset:12288
	s_waitcnt lgkmcnt(1)
	v_mfma_f32_32x32x16_bf16 v[80:95], v[228:231], v[104:107], v[80:95]
	ds_read_b128 v[228:231], v232 offset:8192
	s_waitcnt lgkmcnt(1)
	v_mfma_f32_32x32x16_bf16 v[64:79], v[224:227], v[104:107], v[64:79]
	ds_read_b128 v[224:227], v232 offset:12288
	s_waitcnt lgkmcnt(1)
	v_mfma_f32_32x32x16_bf16 v[80:95], v[228:231], v[100:103], v[80:95]
	ds_read_b128 v[228:231], v233 offset:8192
	s_waitcnt lgkmcnt(1)
	v_mfma_f32_32x32x16_bf16 v[64:79], v[224:227], v[100:103], v[64:79]
	ds_read_b128 v[224:227], v233 offset:12288
	ds_read_b64_tr_b16 v[212:213], v189 offset:0
	ds_read_b64_tr_b16 v[214:215], v189 offset:0x800
	ds_read_b64_tr_b16 v[216:217], v189 offset:0x1000
	ds_read_b64_tr_b16 v[218:219], v189 offset:0x1800
	ds_read_b64_tr_b16 v[220:221], v189 offset:0x2000
	ds_read_b64_tr_b16 v[222:223], v189 offset:0x2800
	s_waitcnt lgkmcnt(7)
	v_mfma_f32_32x32x16_bf16 v[80:95], v[228:231], v[96:99], v[80:95]
	s_waitcnt lgkmcnt(6)
	v_mfma_f32_32x32x16_bf16 v[64:79], v[224:227], v[96:99], v[64:79]
	ds_read_b64_tr_b16 v[224:225], v189 offset:0x3000
	ds_read_b64_tr_b16 v[226:227], v189 offset:0x3800
	s_waitcnt lgkmcnt(4)
	v_mfma_f32_32x32x16_bf16 v[0:15], v[136:139], v[212:215], v[0:15]
	ds_read_b64_tr_b16 v[212:213], v189 offset:0x200
	ds_read_b64_tr_b16 v[214:215], v189 offset:0xa00
	v_mfma_f32_32x32x16_bf16 v[0:15], v[140:143], v[216:219], v[0:15]
	ds_read_b64_tr_b16 v[216:217], v189 offset:0x1200
	ds_read_b64_tr_b16 v[218:219], v189 offset:0x1a00
	v_max3_f32 v250, v80, v81, v82
	v_max3_f32 v250, v250, v83, v84
	v_max3_f32 v250, v250, v85, v86
	v_max3_f32 v250, v250, v87, v88
	v_max3_f32 v250, v250, v89, v90
	v_max3_f32 v250, v250, v91, v92
	s_waitcnt lgkmcnt(4)
	v_mfma_f32_32x32x16_bf16 v[0:15], v[144:147], v[220:223], v[0:15]
	ds_read_b64_tr_b16 v[220:221], v189 offset:0x2200
	ds_read_b64_tr_b16 v[222:223], v189 offset:0x2a00
	v_max3_f32 v250, v250, v93, v94
	v_max3_f32 v250, v250, v95, v64
	v_max3_f32 v250, v250, v65, v66
	v_max3_f32 v250, v250, v67, v68
	v_max3_f32 v250, v250, v69, v70
	v_max3_f32 v250, v250, v71, v72
	v_mfma_f32_32x32x16_bf16 v[0:15], v[148:151], v[224:227], v[0:15]
	ds_read_b64_tr_b16 v[224:225], v189 offset:0x3200
	ds_read_b64_tr_b16 v[226:227], v189 offset:0x3a00
	v_max3_f32 v250, v250, v73, v74
	v_max3_f32 v250, v250, v75, v76
	v_max3_f32 v250, v250, v77, v78
	v_max_f32_e32 v250, v250, v79
	v_mov_b32_e32 v251, v250
	s_waitcnt lgkmcnt(4)
	v_mfma_f32_32x32x16_bf16 v[16:31], v[136:139], v[212:215], v[16:31]
	ds_read_b64_tr_b16 v[212:213], v189 offset:0x400
	ds_read_b64_tr_b16 v[214:215], v189 offset:0xc00
	v_permlane32_swap_b32_e32 v250, v251
	v_max_f32_e32 v251, v250, v251
	v_cmp_ge_f32_e32 vcc, s63, v251
	s_cmp_eq_u64 vcc, exec
	s_cbranch_scc0 .Lda1_rare2
.Lda1_cont2:
	v_mfma_f32_32x32x16_bf16 v[16:31], v[140:143], v[216:219], v[16:31]
	ds_read_b64_tr_b16 v[216:217], v189 offset:0x1400
	ds_read_b64_tr_b16 v[218:219], v189 offset:0x1c00
	v_exp_f32_e32 v80, v80
	v_exp_f32_e32 v81, v81
	v_add_f32_e32 v252, 0, v80
	v_exp_f32_e32 v82, v82
	v_add_f32_e32 v252, v81, v252
	v_exp_f32_e32 v83, v83
	v_add_f32_e32 v252, v82, v252
	s_waitcnt lgkmcnt(4)
	v_mfma_f32_32x32x16_bf16 v[16:31], v[144:147], v[220:223], v[16:31]
	ds_read_b64_tr_b16 v[220:221], v189 offset:0x2400
	ds_read_b64_tr_b16 v[222:223], v189 offset:0x2c00
	v_cvt_pk_bf16_f32 v234, v80, v81
	v_exp_f32_e32 v84, v84
	v_add_f32_e32 v252, v83, v252
	v_exp_f32_e32 v85, v85
	v_add_f32_e32 v252, v84, v252
	v_cvt_pk_bf16_f32 v235, v82, v83
	v_exp_f32_e32 v86, v86
	v_add_f32_e32 v252, v85, v252
	v_mfma_f32_32x32x16_bf16 v[16:31], v[148:151], v[224:227], v[16:31]
	ds_read_b64_tr_b16 v[224:225], v189 offset:0x3400
	ds_read_b64_tr_b16 v[226:227], v189 offset:0x3c00
	v_exp_f32_e32 v87, v87
	v_add_f32_e32 v252, v86, v252
	v_cvt_pk_bf16_f32 v236, v84, v85
	v_exp_f32_e32 v88, v88
	v_add_f32_e32 v252, v87, v252
	v_exp_f32_e32 v89, v89
	v_add_f32_e32 v252, v88, v252
	v_cvt_pk_bf16_f32 v237, v86, v87
	s_waitcnt lgkmcnt(4)
	v_mfma_f32_32x32x16_bf16 v[32:47], v[136:139], v[212:215], v[32:47]
	ds_read_b64_tr_b16 v[212:213], v189 offset:0x600
	ds_read_b64_tr_b16 v[214:215], v189 offset:0xe00
	v_exp_f32_e32 v90, v90
	v_add_f32_e32 v252, v89, v252
	v_exp_f32_e32 v91, v91
	v_permlane32_swap_b32_e32 v234, v236
	v_permlane32_swap_b32_e32 v235, v237
	v_add_f32_e32 v252, v90, v252
	v_cvt_pk_bf16_f32 v238, v88, v89
	v_exp_f32_e32 v92, v92
	v_mfma_f32_32x32x16_bf16 v[32:47], v[140:143], v[216:219], v[32:47]
	ds_read_b64_tr_b16 v[216:217], v189 offset:0x1600
	ds_read_b64_tr_b16 v[218:219], v189 offset:0x1e00
	v_add_f32_e32 v252, v91, v252
	v_exp_f32_e32 v93, v93
	v_add_f32_e32 v252, v92, v252
	v_cvt_pk_bf16_f32 v239, v90, v91
	v_exp_f32_e32 v94, v94
	v_add_f32_e32 v252, v93, v252
	v_exp_f32_e32 v95, v95
	v_add_f32_e32 v252, v94, v252
	s_waitcnt lgkmcnt(4)
	v_mfma_f32_32x32x16_bf16 v[32:47], v[144:147], v[220:223], v[32:47]
	ds_read_b64_tr_b16 v[220:221], v189 offset:0x2600
	ds_read_b64_tr_b16 v[222:223], v189 offset:0x2e00
	v_cvt_pk_bf16_f32 v240, v92, v93
	v_exp_f32_e32 v64, v64
	v_add_f32_e32 v252, v95, v252
	v_exp_f32_e32 v65, v65
	v_add_f32_e32 v252, v64, v252
	v_cvt_pk_bf16_f32 v241, v94, v95
	v_exp_f32_e32 v66, v66
	v_add_f32_e32 v252, v65, v252
	v_mfma_f32_32x32x16_bf16 v[32:47], v[148:151], v[224:227], v[32:47]
	ds_read_b64_tr_b16 v[224:225], v189 offset:0x3600
	ds_read_b64_tr_b16 v[226:227], v189 offset:0x3e00
	v_exp_f32_e32 v67, v67
	v_permlane32_swap_b32_e32 v238, v240
	v_permlane32_swap_b32_e32 v239, v241
	v_add_f32_e32 v252, v66, v252
	v_cvt_pk_bf16_f32 v242, v64, v65
	v_exp_f32_e32 v68, v68
	v_add_f32_e32 v252, v67, v252
	v_exp_f32_e32 v69, v69
	s_waitcnt lgkmcnt(4)
	v_mfma_f32_32x32x16_bf16 v[48:63], v[136:139], v[212:215], v[48:63]
	v_add_f32_e32 v252, v68, v252
	v_cvt_pk_bf16_f32 v243, v66, v67
	v_exp_f32_e32 v70, v70
	v_add_f32_e32 v252, v69, v252
	v_exp_f32_e32 v71, v71
	v_add_f32_e32 v252, v70, v252
	v_cvt_pk_bf16_f32 v244, v68, v69
	v_exp_f32_e32 v72, v72
	v_mfma_f32_32x32x16_bf16 v[48:63], v[140:143], v[216:219], v[48:63]
	v_add_f32_e32 v252, v71, v252
	v_exp_f32_e32 v73, v73
	v_add_f32_e32 v252, v72, v252
	v_cvt_pk_bf16_f32 v245, v70, v71
	v_exp_f32_e32 v74, v74
	v_add_f32_e32 v252, v73, v252
	v_exp_f32_e32 v75, v75
	v_permlane32_swap_b32_e32 v242, v244
	s_waitcnt lgkmcnt(0)
	v_mfma_f32_32x32x16_bf16 v[48:63], v[144:147], v[220:223], v[48:63]
	v_permlane32_swap_b32_e32 v243, v245
	v_add_f32_e32 v252, v74, v252
	v_cvt_pk_bf16_f32 v246, v72, v73
	v_exp_f32_e32 v76, v76
	v_add_f32_e32 v252, v75, v252
	v_exp_f32_e32 v77, v77
	v_add_f32_e32 v252, v76, v252
	v_cvt_pk_bf16_f32 v247, v74, v75
	v_exp_f32_e32 v78, v78
	v_mfma_f32_32x32x16_bf16 v[48:63], v[148:151], v[224:227], v[48:63]
	v_add_f32_e32 v252, v77, v252
	v_exp_f32_e32 v79, v79
	v_add_f32_e32 v252, v78, v252
	v_cvt_pk_bf16_f32 v248, v76, v77
	v_add_f32_e32 v252, v79, v252
	v_cvt_pk_bf16_f32 v249, v78, v79
	v_fma_f32 v192, v192, v253, v252
	s_nop 0
	s_nop 0
	v_permlane32_swap_b32_e32 v246, v248
	v_permlane32_swap_b32_e32 v247, v249
.LBB0_67:
	s_add_i32 s10, s49, 0
	s_waitcnt vmcnt(0)
	v_add_u32_e32 v189, s10, v173
	ds_write_b128 v189, v[128:131]
	v_add_u32_e32 v128, s10, v174
	ds_write_b128 v128, v[124:127]
	ds_write_b128 v189, v[112:115] offset:16384
	ds_write_b128 v128, v[116:119] offset:16384
	v_lshl_add_u32 v124, s48, 14, v175
	v_cmp_gt_f32_e32 vcc, 1.0, v253
	ds_write_b128 v124, v[132:135]
	ds_write_b128 v124, v[120:123] offset:8192
	s_cbranch_vccz .LBB0_71
	s_and_saveexec_b64 s[10:11], s[8:9]
	ds_write_b32 v191, v253 offset:128
	s_or_b64 exec, exec, s[10:11]
	s_waitcnt lgkmcnt(0)
	v_add_u32_e32 v251, s59, v152
	ds_read_b128 v[212:215], v251 offset:224
	ds_read_b128 v[216:219], v251 offset:192
	ds_read_b128 v[220:223], v251 offset:160
	ds_read_b128 v[224:227], v251 offset:128
	s_waitcnt lgkmcnt(3)
	v_pk_mul_f32 v[12:13], v[12:13], v[212:213]
	s_waitcnt lgkmcnt(2)
	v_pk_mul_f32 v[8:9], v[8:9], v[216:217]
	s_waitcnt lgkmcnt(1)
	v_pk_mul_f32 v[4:5], v[4:5], v[220:221]
	v_pk_mul_f32 v[14:15], v[14:15], v[214:215]
	v_pk_mul_f32 v[10:11], v[10:11], v[218:219]
	v_pk_mul_f32 v[6:7], v[6:7], v[222:223]
	s_waitcnt lgkmcnt(0)
	v_pk_mul_f32 v[2:3], v[2:3], v[226:227]
	v_pk_mul_f32 v[0:1], v[0:1], v[224:225]
	v_pk_mul_f32 v[28:29], v[28:29], v[212:213]
	v_pk_mul_f32 v[24:25], v[24:25], v[216:217]
	v_pk_mul_f32 v[20:21], v[20:21], v[220:221]
	v_pk_mul_f32 v[30:31], v[30:31], v[214:215]
	v_pk_mul_f32 v[26:27], v[26:27], v[218:219]
	v_pk_mul_f32 v[22:23], v[22:23], v[222:223]
	v_pk_mul_f32 v[18:19], v[18:19], v[226:227]
	v_pk_mul_f32 v[16:17], v[16:17], v[224:225]
	v_pk_mul_f32 v[44:45], v[44:45], v[212:213]
	v_pk_mul_f32 v[40:41], v[40:41], v[216:217]
	v_pk_mul_f32 v[36:37], v[36:37], v[220:221]
	v_pk_mul_f32 v[46:47], v[46:47], v[214:215]
	v_pk_mul_f32 v[42:43], v[42:43], v[218:219]
	v_pk_mul_f32 v[38:39], v[38:39], v[222:223]
	v_pk_mul_f32 v[34:35], v[34:35], v[226:227]
	v_pk_mul_f32 v[32:33], v[32:33], v[224:225]
	v_pk_mul_f32 v[60:61], v[60:61], v[212:213]
	v_pk_mul_f32 v[56:57], v[56:57], v[216:217]
	v_pk_mul_f32 v[52:53], v[52:53], v[220:221]
	v_pk_mul_f32 v[62:63], v[62:63], v[214:215]
	v_pk_mul_f32 v[58:59], v[58:59], v[218:219]
	v_pk_mul_f32 v[54:55], v[54:55], v[222:223]
	v_pk_mul_f32 v[50:51], v[50:51], v[226:227]
	v_pk_mul_f32 v[48:49], v[48:49], v[224:225]
	v_mov_b32_e32 v253, 1.0

.LBB0_76:
	v_mov_b32_e32 v80, 0
	v_mov_b32_e32 v137, 1.0
	v_mov_b32_e32 v206, 0x48f42400
	v_mov_b32_e32 v202, 0x7f800000
	v_mov_b32_e32 v203, 0x37000000
	v_mov_b32_e32 v204, 0xf149f2ca
	v_mov_b32_e32 v205, 1
	v_mov_b32_e32 v210, 0x7fc00000
	ds_read_b128 v[82:85], v177
	v_xor_b32_e32 v64, 0x80000000, v190
	v_mov_b32_e32 v65, v64
	v_mov_b32_e32 v66, v64
	v_mov_b32_e32 v67, v64
	v_mov_b32_e32 v68, v64
	v_mov_b32_e32 v69, v64
	v_mov_b32_e32 v70, v64
	v_mov_b32_e32 v71, v64
	v_mov_b32_e32 v72, v64
	v_mov_b32_e32 v73, v64
	v_mov_b32_e32 v74, v64
	v_mov_b32_e32 v75, v64
	v_mov_b32_e32 v76, v64
	v_mov_b32_e32 v77, v64
	v_mov_b32_e32 v78, v64
	v_mov_b32_e32 v79, v64
	s_nop 0
	s_nop 0
	s_waitcnt lgkmcnt(0)
	v_mfma_f32_32x32x16_bf16 v[64:79], v[82:85], v[108:111], v[64:79]
	ds_read_b128 v[82:85], v176
	s_nop 0
	s_nop 0
	s_nop 0
	s_nop 0
	s_nop 0
	s_waitcnt lgkmcnt(0)
	v_mfma_f32_32x32x16_bf16 v[64:79], v[82:85], v[104:107], v[64:79]
	ds_read_b128 v[82:85], v178
	ds_read_b128 v[86:89], v179
	s_waitcnt lgkmcnt(1)
	v_mfma_f32_32x32x16_bf16 v[64:79], v[82:85], v[100:103], v[64:79]
	s_nop 0
	s_nop 0
	s_nop 0
	s_nop 0
	s_nop 0
	s_nop 0
	s_nop 0
	s_waitcnt lgkmcnt(0)
	v_mfma_f32_32x32x16_bf16 v[64:79], v[86:89], v[96:99], v[64:79]
	s_nop 0
	s_nop 0
	s_nop 0
	s_nop 0
	s_nop 0
	s_nop 0
	s_nop 5
	s_nop 0
	s_nop 0
	s_nop 0
	s_nop 0
	s_nop 0
	s_nop 0
	s_nop 0
	s_nop 0
	s_cmp_lg_u32 0, -1
	s_cselect_b32 s10, 0, 0
	s_add_i32 s10, s10, 0xc000
	v_add_u32_e32 v72, s10, v172
	ds_read_b64_tr_b16 v[94:95], v72 offset:0
	ds_read_b64_tr_b16 v[96:97], v72 offset:0x800
	ds_read_b64_tr_b16 v[98:99], v72 offset:0x1000
	ds_read_b64_tr_b16 v[100:101], v72 offset:0x1800
	ds_read_b64_tr_b16 v[102:103], v72 offset:0x2000
	ds_read_b64_tr_b16 v[104:105], v72 offset:0x2800
	ds_read_b64_tr_b16 v[106:107], v72 offset:0x3000
	ds_read_b64_tr_b16 v[108:109], v72 offset:0x3800
	s_waitcnt lgkmcnt(0)
	s_nop 0
	v_mfma_f32_32x32x16_bf16 v[0:15], v[234:237], v[94:97], v[0:15]
	ds_read_b64_tr_b16 v[94:95], v72 offset:0x200
	ds_read_b64_tr_b16 v[96:97], v72 offset:0xa00
	v_mfma_f32_32x32x16_bf16 v[0:15], v[238:241], v[98:101], v[0:15]
	ds_read_b64_tr_b16 v[98:99], v72 offset:0x1200
	ds_read_b64_tr_b16 v[100:101], v72 offset:0x1a00
	v_mfma_f32_32x32x16_bf16 v[0:15], v[242:245], v[102:105], v[0:15]
	ds_read_b64_tr_b16 v[102:103], v72 offset:0x2200
	ds_read_b64_tr_b16 v[104:105], v72 offset:0x2a00
	v_mfma_f32_32x32x16_bf16 v[0:15], v[246:249], v[106:109], v[0:15]
	ds_read_b64_tr_b16 v[106:107], v72 offset:0x3200
	ds_read_b64_tr_b16 v[108:109], v72 offset:0x3a00
	s_waitcnt lgkmcnt(0)
	v_mfma_f32_32x32x16_bf16 v[16:31], v[234:237], v[94:97], v[16:31]
	ds_read_b64_tr_b16 v[94:95], v72 offset:0x400
	ds_read_b64_tr_b16 v[96:97], v72 offset:0xc00
	v_mfma_f32_32x32x16_bf16 v[16:31], v[238:241], v[98:101], v[16:31]
	ds_read_b64_tr_b16 v[98:99], v72 offset:0x1400
	ds_read_b64_tr_b16 v[100:101], v72 offset:0x1c00
	v_mfma_f32_32x32x16_bf16 v[16:31], v[242:245], v[102:105], v[16:31]
	ds_read_b64_tr_b16 v[102:103], v72 offset:0x2400
	ds_read_b64_tr_b16 v[104:105], v72 offset:0x2c00
	v_mfma_f32_32x32x16_bf16 v[16:31], v[246:249], v[106:109], v[16:31]
	ds_read_b64_tr_b16 v[106:107], v72 offset:0x3400
	ds_read_b64_tr_b16 v[108:109], v72 offset:0x3c00
	s_waitcnt lgkmcnt(0)
	v_mfma_f32_32x32x16_bf16 v[32:47], v[234:237], v[94:97], v[32:47]
	ds_read_b64_tr_b16 v[94:95], v72 offset:0x600
	ds_read_b64_tr_b16 v[96:97], v72 offset:0xe00
	v_mfma_f32_32x32x16_bf16 v[32:47], v[238:241], v[98:101], v[32:47]
	ds_read_b64_tr_b16 v[98:99], v72 offset:0x1600
	ds_read_b64_tr_b16 v[100:101], v72 offset:0x1e00
	v_mfma_f32_32x32x16_bf16 v[32:47], v[242:245], v[102:105], v[32:47]
	ds_read_b64_tr_b16 v[102:103], v72 offset:0x2600
	ds_read_b64_tr_b16 v[104:105], v72 offset:0x2e00
	v_mfma_f32_32x32x16_bf16 v[32:47], v[246:249], v[106:109], v[32:47]
	ds_read_b64_tr_b16 v[106:107], v72 offset:0x3600
	ds_read_b64_tr_b16 v[108:109], v72 offset:0x3e00
	s_waitcnt lgkmcnt(0)
	v_mfma_f32_32x32x16_bf16 v[48:63], v[234:237], v[94:97], v[48:63]
	v_max3_f32 v72, v64, v65, v66
	v_max3_f32 v72, v72, v67, v68
	v_max3_f32 v72, v72, v69, v70
	v_mov_b32_e32 v73, 0xf149f2ca
	v_max3_f32 v72, v72, v71, v73
	v_mov_b32_e32 v78, v72
	s_nop 1
	v_permlane32_swap_b32_e32 v72, v78
	v_mfma_f32_32x32x16_bf16 v[48:63], v[238:241], v[98:101], v[48:63]
	v_max_f32_e32 v72, v72, v72
	v_mfma_f32_32x32x16_bf16 v[48:63], v[242:245], v[102:105], v[48:63]
	v_max_f32_e32 v74, v78, v78
	v_max_f32_e32 v74, v72, v74
	v_cmp_ge_f32_e32 vcc, s63, v74
	s_cmp_eq_u64 vcc, exec
	v_mov_b32_e32 v72, 1.0
	v_mfma_f32_32x32x16_bf16 v[48:63], v[246:249], v[106:109], v[48:63]
	s_cbranch_scc0 .LBB0_145

.LBB0_90:
	v_exp_f32_e32 v238, v80
	v_exp_f32_e32 v240, v81
	v_exp_f32_e32 v241, v82
	v_exp_f32_e32 v243, v83
	v_exp_f32_e32 v244, v84
	v_exp_f32_e32 v133, v64
	v_exp_f32_e32 v132, v66
	v_add_f32_e32 v64, 0, v238
	v_add_f32_e32 v66, 0, v145
	v_exp_f32_e32 v245, v85
	v_add_f32_e32 v64, v240, v64
	v_add_f32_e32 v66, v146, v66
	v_exp_f32_e32 v239, v86
	v_add_f32_e32 v64, v241, v64
	v_add_f32_e32 v66, v147, v66
	v_exp_f32_e32 v242, v87
	v_add_f32_e32 v64, v243, v64
	v_add_f32_e32 v66, v148, v66
	v_exp_f32_e32 v234, v88
	v_add_f32_e32 v64, v244, v64
	v_add_f32_e32 v66, v149, v66
	v_exp_f32_e32 v235, v89
	v_add_f32_e32 v64, v245, v64
	v_add_f32_e32 v66, v150, v66
	v_exp_f32_e32 v236, v90
	v_add_f32_e32 v64, v239, v64
	v_add_f32_e32 v66, v151, v66
	v_exp_f32_e32 v237, v91
	v_add_f32_e32 v64, v242, v64
	v_add_f32_e32 v66, v155, v66
	v_exp_f32_e32 v230, v92
	v_add_f32_e32 v64, v234, v64
	v_add_f32_e32 v66, v168, v66
	v_exp_f32_e32 v232, v93
	v_add_f32_e32 v64, v235, v64
	v_add_f32_e32 v66, v169, v66
	v_exp_f32_e32 v231, v94
	v_add_f32_e32 v64, v236, v64
	v_add_f32_e32 v66, v170, v66
	v_exp_f32_e32 v233, v95
	v_add_f32_e32 v64, v237, v64
	v_add_f32_e32 v66, v171, v66
	v_add_f32_e32 v64, v230, v64
	v_add_f32_e32 v66, v191, v66
	v_exp_f32_e32 v226, v65
	v_add_f32_e32 v64, v232, v64
	v_add_f32_e32 v66, v192, v66
	v_add_f32_e32 v64, v231, v64
	v_add_f32_e32 v66, v195, v66
	v_exp_f32_e32 v134, v67
	v_add_f32_e32 v64, v233, v64
	v_add_f32_e32 v66, v196, v66
	v_exp_f32_e32 v135, v68
	v_add_f32_e32 v64, v133, v64
	v_add_f32_e32 v66, v197, v66
	v_exp_f32_e32 v227, v69
	v_add_f32_e32 v64, v226, v64
	v_add_f32_e32 v66, v198, v66
	v_exp_f32_e32 v228, v70
	v_add_f32_e32 v64, v132, v64
	v_add_f32_e32 v66, v199, v66
	v_exp_f32_e32 v229, v71
	v_add_f32_e32 v64, v134, v64
	v_add_f32_e32 v66, v200, v66
	v_exp_f32_e32 v124, v72
	v_add_f32_e32 v64, v135, v64
	v_add_f32_e32 v66, v201, v66
	v_exp_f32_e32 v125, v73
	v_add_f32_e32 v64, v227, v64
	v_add_f32_e32 v66, v211, v66
	v_exp_f32_e32 v126, v74
	v_add_f32_e32 v64, v228, v64
	v_add_f32_e32 v66, v212, v66
	v_exp_f32_e32 v127, v75
	v_add_f32_e32 v64, v229, v64
	v_add_f32_e32 v66, v213, v66
	v_exp_f32_e32 v128, v76
	v_add_f32_e32 v64, v124, v64
	v_add_f32_e32 v66, v214, v66
	v_exp_f32_e32 v129, v77
	v_add_f32_e32 v64, v125, v64
	v_add_f32_e32 v66, v215, v66
	v_exp_f32_e32 v130, v78
	v_add_f32_e32 v64, v126, v64
	v_add_f32_e32 v66, v216, v66
	v_exp_f32_e32 v131, v79
	v_add_f32_e32 v64, v127, v64
	v_add_f32_e32 v66, v217, v66
	s_add_u32 s38, s46, 0x80
	v_add_f32_e32 v64, v128, v64
	v_add_f32_e32 v66, v218, v66
	s_addc_u32 s39, s47, 0
	v_mad_i64_i32 v[156:157], s[8:9], v138, s73, 0
	v_mad_i64_i32 v[158:159], s[8:9], v139, s73, 0
	v_mad_i64_i32 v[160:161], s[8:9], v140, s73, 0
	v_mad_i64_i32 v[162:163], s[8:9], v142, s73, 0
	v_mad_i64_i32 v[164:165], s[8:9], v143, s73, 0
	v_mad_i64_i32 v[166:167], s[8:9], v144, s73, 0
	v_add_f32_e32 v64, v129, v64
	v_add_f32_e32 v66, v219, v66
	s_cmp_lg_u32 0, -1
	v_add_f32_e32 v64, v130, v64
	v_add_f32_e32 v66, v220, v66
	s_cselect_b32 s8, 0, 0
	v_add_f32_e32 v194, v131, v64
	v_bfe_u32 v64, v137, 4, 4
	v_bfe_u32 v65, v137, 3, 4
	v_add_f32_e32 v66, v221, v66
	s_addk_i32 s8, 0x4000
	v_add_f32_e32 v192, 0, v66
	v_add_u32_e32 v195, s8, v188
	v_cmp_gt_u32_e64 s[8:9], 32, v141
	v_lshl_add_u32 v191, v136, 2, s59
	v_mul_u32_u24_e32 v168, 0x1800, v64
	v_mov_b32_e32 v169, v181
	v_mul_u32_u24_e32 v170, 0x1800, v65
	v_mov_b32_e32 v171, v181
	s_mov_b32 s23, 1
	s_mov_b64 s[40:41], 0
	s_waitcnt lgkmcnt(0)
	s_barrier
	v_fma_f32 v192, v192, v193, v194
	v_cvt_pk_bf16_f32 v250, v238, v240
	v_cvt_pk_bf16_f32 v251, v241, v243
	v_cvt_pk_bf16_f32 v252, v244, v245
	v_cvt_pk_bf16_f32 v253, v239, v242
	v_cvt_pk_bf16_f32 v238, v234, v235
	v_cvt_pk_bf16_f32 v239, v236, v237
	v_cvt_pk_bf16_f32 v240, v230, v232
	v_cvt_pk_bf16_f32 v241, v231, v233
	v_cvt_pk_bf16_f32 v242, v133, v226
	v_cvt_pk_bf16_f32 v243, v132, v134
	v_cvt_pk_bf16_f32 v244, v135, v227
	v_cvt_pk_bf16_f32 v245, v228, v229
	v_cvt_pk_bf16_f32 v246, v124, v125
	v_cvt_pk_bf16_f32 v247, v126, v127
	v_cvt_pk_bf16_f32 v248, v128, v129
	v_cvt_pk_bf16_f32 v249, v130, v131
	s_nop 1
	v_permlane32_swap_b32_e32 v250, v252
	v_permlane32_swap_b32_e32 v251, v253
	v_permlane32_swap_b32_e32 v238, v240
	v_permlane32_swap_b32_e32 v239, v241
	v_permlane32_swap_b32_e32 v242, v244
	v_permlane32_swap_b32_e32 v243, v245
	v_permlane32_swap_b32_e32 v246, v248
	v_permlane32_swap_b32_e32 v247, v249
	v_mov_b32_e32 v234, v250
	v_mov_b32_e32 v235, v251
	v_mov_b32_e32 v236, v252
	v_mov_b32_e32 v237, v253
	v_xor_b32_e32 v196, 0x80000000, v190
	v_mov_b32_e32 v197, v196
	v_mov_b32_e32 v198, v196
	v_mov_b32_e32 v199, v196
	v_mov_b32_e32 v200, v196
	v_mov_b32_e32 v201, v196
	v_mov_b32_e32 v202, v196
	v_mov_b32_e32 v203, v196
	v_mov_b32_e32 v204, v196
	v_mov_b32_e32 v205, v196
	v_mov_b32_e32 v206, v196
	v_mov_b32_e32 v207, v196
	v_mov_b32_e32 v208, v196
	v_mov_b32_e32 v209, v196
	v_mov_b32_e32 v210, v196
	v_mov_b32_e32 v211, v196
	v_mov_b32_e32 v253, 1.0
	v_add_u32_e32 v156, v156, v180
	v_add_u32_e32 v158, v158, v180
	v_add_u32_e32 v160, v160, v154
	v_add_u32_e32 v162, v162, v154
	v_add_u32_e32 v164, v164, v180
	v_add_u32_e32 v166, v166, v180
	v_add_u32_e32 v168, v168, v180
	v_add_u32_e32 v170, v170, v154
.LBB0_91:
	s_and_b32 s46, s23, 1
	s_lshl_b32 s10, s46, 14
	s_add_i32 s10, s10, 0x10000
	v_add_u32_e32 v193, s10, v175
	v_add_u32_e32 v194, s10, v182
	v_add_u32_e32 v232, s10, v186
	v_add_u32_e32 v233, s10, v187
	s_xor_b32 s11, s46, 1
	s_lshl_b32 s11, s11, 15
	v_add_u32_e32 v189, s11, v195
	ds_read_b128 v[228:231], v193
	ds_read_b128 v[224:227], v193 offset:4096
	s_waitcnt lgkmcnt(1)
	v_mfma_f32_32x32x16_bf16 v[80:95], v[228:231], v[108:111], v[196:211]
	ds_read_b128 v[228:231], v194
	s_waitcnt lgkmcnt(1)
	v_mfma_f32_32x32x16_bf16 v[64:79], v[224:227], v[108:111], v[196:211]
	ds_read_b128 v[224:227], v194 offset:4096
	s_waitcnt lgkmcnt(1)
	v_mfma_f32_32x32x16_bf16 v[80:95], v[228:231], v[104:107], v[80:95]
	ds_read_b128 v[228:231], v232
	s_waitcnt lgkmcnt(1)
	v_mfma_f32_32x32x16_bf16 v[64:79], v[224:227], v[104:107], v[64:79]
	ds_read_b128 v[224:227], v232 offset:4096
	s_waitcnt lgkmcnt(1)
	v_mfma_f32_32x32x16_bf16 v[80:95], v[228:231], v[100:103], v[80:95]
	ds_read_b128 v[228:231], v233
	s_waitcnt lgkmcnt(1)
	v_mfma_f32_32x32x16_bf16 v[64:79], v[224:227], v[100:103], v[64:79]
	ds_read_b128 v[224:227], v233 offset:4096
	ds_read_b64_tr_b16 v[212:213], v189 offset:0
	ds_read_b64_tr_b16 v[214:215], v189 offset:0x800
	ds_read_b64_tr_b16 v[216:217], v189 offset:0x1000
	ds_read_b64_tr_b16 v[218:219], v189 offset:0x1800
	ds_read_b64_tr_b16 v[220:221], v189 offset:0x2000
	ds_read_b64_tr_b16 v[222:223], v189 offset:0x2800
	s_waitcnt lgkmcnt(7)
	v_mfma_f32_32x32x16_bf16 v[80:95], v[228:231], v[96:99], v[80:95]
	s_waitcnt lgkmcnt(6)
	v_mfma_f32_32x32x16_bf16 v[64:79], v[224:227], v[96:99], v[64:79]
	ds_read_b64_tr_b16 v[224:225], v189 offset:0x3000
	ds_read_b64_tr_b16 v[226:227], v189 offset:0x3800
	s_cmp_eq_u32 s67, s40
	s_cbranch_scc1 .Lda2_sl_last
	s_add_u32 s10, s77, s40
	s_addc_u32 s11, s66, s41
	s_add_u32 s42, s10, 0x126c3400
	s_addc_u32 s43, s11, 0
	s_add_u32 s25, s77, s40
	s_addc_u32 s45, s66, s41
	s_add_u32 s44, s25, 0x126c2c80
	s_addc_u32 s45, s45, 0
	global_load_dwordx4 v[128:131], v156, s[42:43]
	global_load_dwordx4 v[124:127], v158, s[42:43]
	global_load_dwordx4 v[132:135], v160, s[44:45]
	global_load_dwordx4 v[112:115], v166, s[42:43]
	global_load_dwordx4 v[116:119], v164, s[42:43]
	global_load_dwordx4 v[120:123], v162, s[44:45]
	s_branch .LBB0_97
.Lda2_sl_last:
	global_load_dwordx4 v[128:131], v168, s[20:21]
	global_load_dwordx4 v[124:127], v168, s[20:21]
	global_load_dwordx4 v[132:135], v170, s[38:39]
.LBB0_97:
	s_xor_b32 s25, s46, 1
	s_lshl_b32 s42, s25, 15
	s_waitcnt lgkmcnt(4)
	v_mfma_f32_32x32x16_bf16 v[0:15], v[234:237], v[212:215], v[0:15]
	ds_read_b64_tr_b16 v[212:213], v189 offset:0x200
	ds_read_b64_tr_b16 v[214:215], v189 offset:0xa00
	v_mfma_f32_32x32x16_bf16 v[0:15], v[238:241], v[216:219], v[0:15]
	ds_read_b64_tr_b16 v[216:217], v189 offset:0x1200
	ds_read_b64_tr_b16 v[218:219], v189 offset:0x1a00
	v_max3_f32 v250, v80, v81, v82
	v_max3_f32 v250, v250, v83, v84
	v_max3_f32 v250, v250, v85, v86
	v_max3_f32 v250, v250, v87, v88
	v_max3_f32 v250, v250, v89, v90
	v_max3_f32 v250, v250, v91, v92
	s_waitcnt lgkmcnt(4)
	v_mfma_f32_32x32x16_bf16 v[0:15], v[242:245], v[220:223], v[0:15]
	ds_read_b64_tr_b16 v[220:221], v189 offset:0x2200
	ds_read_b64_tr_b16 v[222:223], v189 offset:0x2a00
	v_max3_f32 v250, v250, v93, v94
	v_max3_f32 v250, v250, v95, v64
	v_max3_f32 v250, v250, v65, v66
	v_max3_f32 v250, v250, v67, v68
	v_max3_f32 v250, v250, v69, v70
	v_max3_f32 v250, v250, v71, v72
	v_mfma_f32_32x32x16_bf16 v[0:15], v[246:249], v[224:227], v[0:15]
	ds_read_b64_tr_b16 v[224:225], v189 offset:0x3200
	ds_read_b64_tr_b16 v[226:227], v189 offset:0x3a00
	v_max3_f32 v250, v250, v73, v74
	v_max3_f32 v250, v250, v75, v76
	v_max3_f32 v250, v250, v77, v78
	v_max_f32_e32 v250, v250, v79
	v_mov_b32_e32 v251, v250
	s_waitcnt lgkmcnt(4)
	v_mfma_f32_32x32x16_bf16 v[16:31], v[234:237], v[212:215], v[16:31]
	ds_read_b64_tr_b16 v[212:213], v189 offset:0x400
	ds_read_b64_tr_b16 v[214:215], v189 offset:0xc00
	v_permlane32_swap_b32_e32 v250, v251
	v_max_f32_e32 v251, v250, v251
	v_cmp_ge_f32_e32 vcc, s63, v251
	s_cmp_eq_u64 vcc, exec
	s_cbranch_scc0 .Lda2_rare1

.LBB0_102:
	v_lshl_add_u32 v189, s46, 15, v153
	s_waitcnt lgkmcnt(1)
	v_mfma_f32_32x32x16_bf16 v[80:95], v[228:231], v[108:111], v[196:211]
	ds_read_b128 v[228:231], v194 offset:8192
	s_waitcnt lgkmcnt(1)
	v_mfma_f32_32x32x16_bf16 v[64:79], v[224:227], v[108:111], v[196:211]
	ds_read_b128 v[224:227], v194 offset:12288
	s_waitcnt lgkmcnt(1)
	v_mfma_f32_32x32x16_bf16 v[80:95], v[228:231], v[104:107], v[80:95]
	ds_read_b128 v[228:231], v232 offset:8192
	s_waitcnt lgkmcnt(1)
	v_mfma_f32_32x32x16_bf16 v[64:79], v[224:227], v[104:107], v[64:79]
	ds_read_b128 v[224:227], v232 offset:12288
	s_waitcnt lgkmcnt(1)
	v_mfma_f32_32x32x16_bf16 v[80:95], v[228:231], v[100:103], v[80:95]
	ds_read_b128 v[228:231], v233 offset:8192
	s_waitcnt lgkmcnt(1)
	v_mfma_f32_32x32x16_bf16 v[64:79], v[224:227], v[100:103], v[64:79]
	ds_read_b128 v[224:227], v233 offset:12288
	ds_read_b64_tr_b16 v[212:213], v189 offset:0
	ds_read_b64_tr_b16 v[214:215], v189 offset:0x800
	ds_read_b64_tr_b16 v[216:217], v189 offset:0x1000
	ds_read_b64_tr_b16 v[218:219], v189 offset:0x1800
	ds_read_b64_tr_b16 v[220:221], v189 offset:0x2000
	ds_read_b64_tr_b16 v[222:223], v189 offset:0x2800
	s_waitcnt lgkmcnt(7)
	v_mfma_f32_32x32x16_bf16 v[80:95], v[228:231], v[96:99], v[80:95]
	s_waitcnt lgkmcnt(6)
	v_mfma_f32_32x32x16_bf16 v[64:79], v[224:227], v[96:99], v[64:79]
	ds_read_b64_tr_b16 v[224:225], v189 offset:0x3000
	ds_read_b64_tr_b16 v[226:227], v189 offset:0x3800
	s_waitcnt lgkmcnt(4)
	v_mfma_f32_32x32x16_bf16 v[0:15], v[136:139], v[212:215], v[0:15]
	ds_read_b64_tr_b16 v[212:213], v189 offset:0x200
	ds_read_b64_tr_b16 v[214:215], v189 offset:0xa00
	v_mfma_f32_32x32x16_bf16 v[0:15], v[140:143], v[216:219], v[0:15]
	ds_read_b64_tr_b16 v[216:217], v189 offset:0x1200
	ds_read_b64_tr_b16 v[218:219], v189 offset:0x1a00
	v_max3_f32 v250, v80, v81, v82
	v_max3_f32 v250, v250, v83, v84
	v_max3_f32 v250, v250, v85, v86
	v_max3_f32 v250, v250, v87, v88
	v_max3_f32 v250, v250, v89, v90
	v_max3_f32 v250, v250, v91, v92
	s_waitcnt lgkmcnt(4)
	v_mfma_f32_32x32x16_bf16 v[0:15], v[144:147], v[220:223], v[0:15]
	ds_read_b64_tr_b16 v[220:221], v189 offset:0x2200
	ds_read_b64_tr_b16 v[222:223], v189 offset:0x2a00
	v_max3_f32 v250, v250, v93, v94
	v_max3_f32 v250, v250, v95, v64
	v_max3_f32 v250, v250, v65, v66
	v_max3_f32 v250, v250, v67, v68
	v_max3_f32 v250, v250, v69, v70
	v_max3_f32 v250, v250, v71, v72
	v_mfma_f32_32x32x16_bf16 v[0:15], v[148:151], v[224:227], v[0:15]
	ds_read_b64_tr_b16 v[224:225], v189 offset:0x3200
	ds_read_b64_tr_b16 v[226:227], v189 offset:0x3a00
	v_max3_f32 v250, v250, v73, v74
	v_max3_f32 v250, v250, v75, v76
	v_max3_f32 v250, v250, v77, v78
	v_max_f32_e32 v250, v250, v79
	v_mov_b32_e32 v251, v250
	s_waitcnt lgkmcnt(4)
	v_mfma_f32_32x32x16_bf16 v[16:31], v[136:139], v[212:215], v[16:31]
	ds_read_b64_tr_b16 v[212:213], v189 offset:0x400
	ds_read_b64_tr_b16 v[214:215], v189 offset:0xc00
	v_permlane32_swap_b32_e32 v250, v251
	v_max_f32_e32 v251, v250, v251
	v_cmp_ge_f32_e32 vcc, s63, v251
	s_cmp_eq_u64 vcc, exec
	s_cbranch_scc0 .Lda2_rare2

.LBB0_103:
	s_add_i32 s10, s42, 0
	s_waitcnt vmcnt(0)
	v_add_u32_e32 v189, s10, v178
	ds_write_b128 v189, v[128:131]
	v_add_u32_e32 v128, s10, v179
	ds_write_b128 v128, v[124:127]
	ds_write_b128 v189, v[112:115] offset:16384
	ds_write_b128 v128, v[116:119] offset:16384
	v_lshl_add_u32 v124, s25, 14, v177
	v_cmp_gt_f32_e32 vcc, 1.0, v253
	ds_write_b128 v124, v[132:135]
	ds_write_b128 v124, v[120:123] offset:8192
	s_cbranch_vccz .LBB0_107
	s_and_saveexec_b64 s[10:11], s[8:9]
	ds_write_b32 v191, v253 offset:128
	s_or_b64 exec, exec, s[10:11]
	s_waitcnt lgkmcnt(0)
	v_add_u32_e32 v251, s59, v152
	ds_read_b128 v[212:215], v251 offset:224
	ds_read_b128 v[216:219], v251 offset:192
	ds_read_b128 v[220:223], v251 offset:160
	ds_read_b128 v[224:227], v251 offset:128
	s_waitcnt lgkmcnt(3)
	v_pk_mul_f32 v[12:13], v[12:13], v[212:213]
	s_waitcnt lgkmcnt(2)
	v_pk_mul_f32 v[8:9], v[8:9], v[216:217]
	s_waitcnt lgkmcnt(1)
	v_pk_mul_f32 v[4:5], v[4:5], v[220:221]
	v_pk_mul_f32 v[14:15], v[14:15], v[214:215]
	v_pk_mul_f32 v[10:11], v[10:11], v[218:219]
	v_pk_mul_f32 v[6:7], v[6:7], v[222:223]
	s_waitcnt lgkmcnt(0)
	v_pk_mul_f32 v[2:3], v[2:3], v[226:227]
	v_pk_mul_f32 v[0:1], v[0:1], v[224:225]
	v_pk_mul_f32 v[28:29], v[28:29], v[212:213]
	v_pk_mul_f32 v[24:25], v[24:25], v[216:217]
	v_pk_mul_f32 v[20:21], v[20:21], v[220:221]
	v_pk_mul_f32 v[30:31], v[30:31], v[214:215]
	v_pk_mul_f32 v[26:27], v[26:27], v[218:219]
	v_pk_mul_f32 v[22:23], v[22:23], v[222:223]
	v_pk_mul_f32 v[18:19], v[18:19], v[226:227]
	v_pk_mul_f32 v[16:17], v[16:17], v[224:225]
	v_pk_mul_f32 v[44:45], v[44:45], v[212:213]
	v_pk_mul_f32 v[40:41], v[40:41], v[216:217]
	v_pk_mul_f32 v[36:37], v[36:37], v[220:221]
	v_pk_mul_f32 v[46:47], v[46:47], v[214:215]
	v_pk_mul_f32 v[42:43], v[42:43], v[218:219]
	v_pk_mul_f32 v[38:39], v[38:39], v[222:223]
	v_pk_mul_f32 v[34:35], v[34:35], v[226:227]
	v_pk_mul_f32 v[32:33], v[32:33], v[224:225]
	v_pk_mul_f32 v[60:61], v[60:61], v[212:213]
	v_pk_mul_f32 v[56:57], v[56:57], v[216:217]
	v_pk_mul_f32 v[52:53], v[52:53], v[220:221]
	v_pk_mul_f32 v[62:63], v[62:63], v[214:215]
	v_pk_mul_f32 v[58:59], v[58:59], v[218:219]
	v_pk_mul_f32 v[54:55], v[54:55], v[222:223]
	v_pk_mul_f32 v[50:51], v[50:51], v[226:227]
	v_pk_mul_f32 v[48:49], v[48:49], v[224:225]
	v_mov_b32_e32 v253, 1.0

.LBB0_111:
	v_mov_b32_e32 v80, 0
	v_mov_b32_e32 v137, 1.0
	v_mov_b32_e32 v206, 0x48f42400
	v_mov_b32_e32 v202, 0x7f800000
	v_mov_b32_e32 v203, 0x37000000
	v_mov_b32_e32 v204, 0xf149f2ca
	v_mov_b32_e32 v205, 1
	v_mov_b32_e32 v210, 0x7fc00000
	ds_read_b128 v[82:85], v172
	v_xor_b32_e32 v64, 0x80000000, v190
	v_mov_b32_e32 v65, v64
	v_mov_b32_e32 v66, v64
	v_mov_b32_e32 v67, v64
	v_mov_b32_e32 v68, v64
	v_mov_b32_e32 v69, v64
	v_mov_b32_e32 v70, v64
	v_mov_b32_e32 v71, v64
	v_mov_b32_e32 v72, v64
	v_mov_b32_e32 v73, v64
	v_mov_b32_e32 v74, v64
	v_mov_b32_e32 v75, v64
	v_mov_b32_e32 v76, v64
	v_mov_b32_e32 v77, v64
	v_mov_b32_e32 v78, v64
	v_mov_b32_e32 v79, v64
	s_nop 0
	s_nop 0
	s_waitcnt lgkmcnt(0)
	v_mfma_f32_32x32x16_bf16 v[64:79], v[82:85], v[108:111], v[64:79]
	ds_read_b128 v[82:85], v173
	s_nop 0
	s_nop 0
	s_nop 0
	s_nop 0
	s_nop 0
	s_waitcnt lgkmcnt(0)
	v_mfma_f32_32x32x16_bf16 v[64:79], v[82:85], v[104:107], v[64:79]
	ds_read_b128 v[82:85], v174
	ds_read_b128 v[86:89], v176
	s_waitcnt lgkmcnt(1)
	v_mfma_f32_32x32x16_bf16 v[64:79], v[82:85], v[100:103], v[64:79]
	s_nop 0
	s_nop 0
	s_nop 0
	s_nop 0
	s_nop 0
	s_nop 0
	s_nop 0
	s_waitcnt lgkmcnt(0)
	v_mfma_f32_32x32x16_bf16 v[64:79], v[86:89], v[96:99], v[64:79]
	s_nop 0
	s_nop 0
	s_nop 0
	s_nop 0
	s_nop 0
	s_nop 0
	s_nop 5
	s_nop 0
	s_nop 0
	s_nop 0
	s_nop 0
	s_nop 0
	s_nop 0
	s_nop 0
	s_nop 0
	s_cmp_lg_u32 0, -1
	s_cselect_b32 s10, 0, 0
	s_add_i32 s10, s10, 0xc000
	v_add_u32_e32 v72, s10, v188
	ds_read_b64_tr_b16 v[94:95], v72 offset:0
	ds_read_b64_tr_b16 v[96:97], v72 offset:0x800
	ds_read_b64_tr_b16 v[98:99], v72 offset:0x1000
	ds_read_b64_tr_b16 v[100:101], v72 offset:0x1800
	ds_read_b64_tr_b16 v[102:103], v72 offset:0x2000
	ds_read_b64_tr_b16 v[104:105], v72 offset:0x2800
	ds_read_b64_tr_b16 v[106:107], v72 offset:0x3000
	ds_read_b64_tr_b16 v[108:109], v72 offset:0x3800
	s_waitcnt lgkmcnt(0)
	s_nop 0
	v_mfma_f32_32x32x16_bf16 v[0:15], v[234:237], v[94:97], v[0:15]
	ds_read_b64_tr_b16 v[94:95], v72 offset:0x200
	ds_read_b64_tr_b16 v[96:97], v72 offset:0xa00
	v_mfma_f32_32x32x16_bf16 v[0:15], v[238:241], v[98:101], v[0:15]
	ds_read_b64_tr_b16 v[98:99], v72 offset:0x1200
	ds_read_b64_tr_b16 v[100:101], v72 offset:0x1a00
	v_mfma_f32_32x32x16_bf16 v[0:15], v[242:245], v[102:105], v[0:15]
	ds_read_b64_tr_b16 v[102:103], v72 offset:0x2200
	ds_read_b64_tr_b16 v[104:105], v72 offset:0x2a00
	v_mfma_f32_32x32x16_bf16 v[0:15], v[246:249], v[106:109], v[0:15]
	ds_read_b64_tr_b16 v[106:107], v72 offset:0x3200
	ds_read_b64_tr_b16 v[108:109], v72 offset:0x3a00
	s_waitcnt lgkmcnt(0)
	v_mfma_f32_32x32x16_bf16 v[16:31], v[234:237], v[94:97], v[16:31]
	ds_read_b64_tr_b16 v[94:95], v72 offset:0x400
	ds_read_b64_tr_b16 v[96:97], v72 offset:0xc00
	v_mfma_f32_32x32x16_bf16 v[16:31], v[238:241], v[98:101], v[16:31]
	ds_read_b64_tr_b16 v[98:99], v72 offset:0x1400
	ds_read_b64_tr_b16 v[100:101], v72 offset:0x1c00
	v_mfma_f32_32x32x16_bf16 v[16:31], v[242:245], v[102:105], v[16:31]
	ds_read_b64_tr_b16 v[102:103], v72 offset:0x2400
	ds_read_b64_tr_b16 v[104:105], v72 offset:0x2c00
	v_mfma_f32_32x32x16_bf16 v[16:31], v[246:249], v[106:109], v[16:31]
	ds_read_b64_tr_b16 v[106:107], v72 offset:0x3400
	ds_read_b64_tr_b16 v[108:109], v72 offset:0x3c00
	s_waitcnt lgkmcnt(0)
	v_mfma_f32_32x32x16_bf16 v[32:47], v[234:237], v[94:97], v[32:47]
	ds_read_b64_tr_b16 v[94:95], v72 offset:0x600
	ds_read_b64_tr_b16 v[96:97], v72 offset:0xe00
	v_mfma_f32_32x32x16_bf16 v[32:47], v[238:241], v[98:101], v[32:47]
	ds_read_b64_tr_b16 v[98:99], v72 offset:0x1600
	ds_read_b64_tr_b16 v[100:101], v72 offset:0x1e00
	v_mfma_f32_32x32x16_bf16 v[32:47], v[242:245], v[102:105], v[32:47]
	ds_read_b64_tr_b16 v[102:103], v72 offset:0x2600
	ds_read_b64_tr_b16 v[104:105], v72 offset:0x2e00
	v_mfma_f32_32x32x16_bf16 v[32:47], v[246:249], v[106:109], v[32:47]
	ds_read_b64_tr_b16 v[106:107], v72 offset:0x3600
	ds_read_b64_tr_b16 v[108:109], v72 offset:0x3e00
	s_waitcnt lgkmcnt(0)
	v_mfma_f32_32x32x16_bf16 v[48:63], v[234:237], v[94:97], v[48:63]
	v_max3_f32 v72, v64, v65, v66
	v_max3_f32 v72, v72, v67, v68
	v_max3_f32 v72, v72, v69, v70
	v_mov_b32_e32 v73, 0xf149f2ca
	v_max3_f32 v72, v72, v71, v73
	v_mov_b32_e32 v78, v72
	s_nop 1
	v_permlane32_swap_b32_e32 v72, v78
	v_mfma_f32_32x32x16_bf16 v[48:63], v[238:241], v[98:101], v[48:63]
	v_max_f32_e32 v72, v72, v72
	v_mov_b32_e32 v211, v206
	v_mfma_f32_32x32x16_bf16 v[48:63], v[242:245], v[102:105], v[48:63]
	v_max_f32_e32 v74, v78, v78
	v_max_f32_e32 v74, v72, v74
	v_cmp_ge_f32_e32 vcc, s63, v74
	s_cmp_eq_u64 vcc, exec
	v_mov_b32_e32 v72, 1.0
	v_mfma_f32_32x32x16_bf16 v[48:63], v[246:249], v[106:109], v[48:63]
	s_cbranch_scc0 .LBB0_147
	v_cmp_gt_f32_e32 vcc, 1.0, v72
	s_cbranch_vccz .LBB0_116

.LBB0_122:
	s_add_i32 s8, s40, s36
	ds_read_b128 v[160:163], v215 offset:49152
	ds_read_b128 v[164:167], v215 offset:57344
	v_xor_b32_e32 v80, 0x80000000, v235
	v_mov_b32_e32 v81, v80
	v_mov_b32_e32 v82, v80
	v_mov_b32_e32 v83, v80
	v_mov_b32_e32 v84, v80
	v_mov_b32_e32 v85, v80
	v_mov_b32_e32 v86, v80
	v_mov_b32_e32 v87, v80
	v_mov_b32_e32 v88, v80
	v_mov_b32_e32 v89, v80
	v_mov_b32_e32 v90, v80
	v_mov_b32_e32 v91, v80
	v_mov_b32_e32 v92, v80
	v_mov_b32_e32 v93, v80
	v_mov_b32_e32 v94, v80
	v_mov_b32_e32 v95, v80
	s_add_i32 s9, 0, 0x12000
	v_exp_f32_e32 v78, v78
	s_waitcnt lgkmcnt(1)
	v_mfma_f32_32x32x16_bf16 v[96:111], v[160:163], v[128:131], v[80:95]
	v_exp_f32_e32 v79, v79
	v_exp_f32_e32 v76, v76
	v_exp_f32_e32 v77, v77
	v_exp_f32_e32 v74, v74
	v_exp_f32_e32 v75, v75
	s_waitcnt lgkmcnt(0)
	v_mfma_f32_32x32x16_bf16 v[80:95], v[164:167], v[128:131], v[80:95]
	ds_read_b128 v[160:163], v216 offset:49152
	ds_read_b128 v[164:167], v216 offset:57344
	s_waitcnt lgkmcnt(1)
	v_mfma_f32_32x32x16_bf16 v[96:111], v[160:163], v[132:135], v[96:111]
	ds_read_b128 v[160:163], v217 offset:49152
	s_waitcnt lgkmcnt(1)
	v_mfma_f32_32x32x16_bf16 v[80:95], v[164:167], v[132:135], v[80:95]
	ds_read_b128 v[164:167], v217 offset:57344
	s_waitcnt lgkmcnt(1)
	v_mfma_f32_32x32x16_bf16 v[96:111], v[160:163], v[136:139], v[96:111]
	ds_read_b128 v[160:163], v218 offset:49152
	s_waitcnt lgkmcnt(1)
	v_mfma_f32_32x32x16_bf16 v[80:95], v[164:167], v[136:139], v[80:95]
	ds_read_b128 v[164:167], v218 offset:57344
	s_waitcnt lgkmcnt(1)
	v_mfma_f32_32x32x16_bf16 v[96:111], v[160:163], v[140:143], v[96:111]
	ds_read_b128 v[160:163], v219 offset:49152
	s_waitcnt lgkmcnt(1)
	v_mfma_f32_32x32x16_bf16 v[80:95], v[164:167], v[140:143], v[80:95]
	ds_read_b128 v[164:167], v219 offset:57344
	s_waitcnt lgkmcnt(1)
	v_mfma_f32_32x32x16_bf16 v[96:111], v[160:163], v[144:147], v[96:111]
	ds_read_b128 v[160:163], v220 offset:49152
	s_waitcnt lgkmcnt(1)
	v_mfma_f32_32x32x16_bf16 v[80:95], v[164:167], v[144:147], v[80:95]
	ds_read_b128 v[164:167], v220 offset:57344
	s_waitcnt lgkmcnt(1)
	v_mfma_f32_32x32x16_bf16 v[96:111], v[160:163], v[148:151], v[96:111]
	ds_read_b128 v[160:163], v221 offset:49152
	s_waitcnt lgkmcnt(1)
	v_mfma_f32_32x32x16_bf16 v[80:95], v[164:167], v[148:151], v[80:95]
	ds_read_b128 v[164:167], v221 offset:57344
	s_waitcnt lgkmcnt(1)
	v_mfma_f32_32x32x16_bf16 v[96:111], v[160:163], v[152:155], v[96:111]
	ds_read_b128 v[160:163], v222 offset:49152
	s_waitcnt lgkmcnt(1)
	v_mfma_f32_32x32x16_bf16 v[80:95], v[164:167], v[152:155], v[80:95]
	ds_read_b128 v[164:167], v222 offset:57344
	s_waitcnt lgkmcnt(1)
	v_mfma_f32_32x32x16_bf16 v[96:111], v[160:163], v[156:159], v[96:111]
	s_waitcnt lgkmcnt(0)
	v_mfma_f32_32x32x16_bf16 v[80:95], v[164:167], v[156:159], v[80:95]
	v_add_u32_e32 v164, s9, v223
	ds_read_b128 v[160:163], v164
	ds_read_b128 v[164:167], v164 offset:4096
	ds_read_b128 v[168:171], v225
	s_waitcnt lgkmcnt(0)
	v_mfma_f32_32x32x16_bf16 v[96:111], v[160:163], v[168:171], v[96:111]
	v_mfma_f32_32x32x16_bf16 v[80:95], v[164:167], v[168:171], v[80:95]
	v_add_u32_e32 v164, s9, v226
	ds_read_b128 v[160:163], v164
	ds_read_b128 v[164:167], v164 offset:4096
	ds_read_b128 v[168:171], v228
	s_waitcnt lgkmcnt(0)
	v_mfma_f32_32x32x16_bf16 v[96:111], v[160:163], v[168:171], v[96:111]
	v_mfma_f32_32x32x16_bf16 v[80:95], v[164:167], v[168:171], v[80:95]
	v_add_u32_e32 v164, s9, v229
	ds_read_b128 v[160:163], v164
	ds_read_b128 v[164:167], v164 offset:4096
	ds_read_b128 v[168:171], v231
	s_waitcnt lgkmcnt(0)
	v_mfma_f32_32x32x16_bf16 v[96:111], v[160:163], v[168:171], v[96:111]
	v_mfma_f32_32x32x16_bf16 v[80:95], v[164:167], v[168:171], v[80:95]
	v_add_u32_e32 v164, s9, v232
	ds_read_b128 v[160:163], v164
	ds_read_b128 v[164:167], v164 offset:4096
	ds_read_b128 v[168:171], v234
	s_waitcnt lgkmcnt(0)
	v_mfma_f32_32x32x16_bf16 v[96:111], v[160:163], v[168:171], v[96:111]
	v_exp_f32_e32 v160, v72
	v_exp_f32_e32 v161, v73
	v_exp_f32_e32 v162, v70
	v_exp_f32_e32 v163, v71
	v_cvt_pk_bf16_f32 v70, v113, v116
	v_cvt_pk_bf16_f32 v71, v117, v119
	v_cvt_pk_bf16_f32 v72, v78, v79
	v_mfma_f32_32x32x16_bf16 v[80:95], v[164:167], v[168:171], v[80:95]
	v_exp_f32_e32 v168, v64
	v_add_f32_e32 v64, 0, v120
	v_add_f32_e32 v64, v121, v64
	v_add_f32_e32 v64, v122, v64
	v_add_f32_e32 v64, v124, v64
	v_add_f32_e32 v64, v125, v64
	v_add_f32_e32 v64, v127, v64
	v_add_f32_e32 v64, v123, v64
	v_add_f32_e32 v64, v126, v64
	v_add_f32_e32 v64, v112, v64
	v_add_f32_e32 v64, v114, v64
	v_add_f32_e32 v64, v115, v64
	v_add_f32_e32 v64, v118, v64
	v_add_f32_e32 v64, v113, v64
	v_add_f32_e32 v64, v116, v64
	v_add_f32_e32 v64, v117, v64
	v_add_f32_e32 v64, v119, v64
	v_add_f32_e32 v64, v78, v64
	v_add_f32_e32 v64, v79, v64
	v_add_f32_e32 v64, v76, v64
	v_add_f32_e32 v64, v77, v64
	v_add_f32_e32 v64, v74, v64
	v_add_f32_e32 v64, v75, v64
	v_exp_f32_e32 v164, v68
	v_add_f32_e32 v64, v160, v64
	v_exp_f32_e32 v165, v69
	v_add_f32_e32 v64, v161, v64
	v_exp_f32_e32 v166, v66
	v_add_f32_e32 v64, v162, v64
	v_exp_f32_e32 v167, v67
	v_add_f32_e32 v64, v163, v64
	v_add_f32_e32 v64, v164, v64
	v_exp_f32_e32 v169, v65
	v_add_f32_e32 v64, v165, v64
	v_add_f32_e32 v64, v166, v64
	v_add_f32_e32 v64, v167, v64
	v_add_f32_e32 v64, v168, v64
	v_add_f32_e32 v242, v169, v64
	v_mov_b32_e32 v243, v242
	v_cvt_pk_bf16_f32 v64, v120, v121
	v_cvt_pk_bf16_f32 v65, v122, v124
	v_cvt_pk_bf16_f32 v66, v125, v127
	v_cvt_pk_bf16_f32 v67, v123, v126
	v_cvt_pk_bf16_f32 v68, v112, v114
	v_cvt_pk_bf16_f32 v69, v115, v118
	v_cvt_pk_bf16_f32 v73, v76, v77
	v_cvt_pk_bf16_f32 v74, v74, v75
	v_cvt_pk_bf16_f32 v75, v160, v161
	v_cvt_pk_bf16_f32 v76, v162, v163
	v_cvt_pk_bf16_f32 v77, v164, v165
	v_cvt_pk_bf16_f32 v78, v166, v167
	v_cvt_pk_bf16_f32 v79, v168, v169
	v_permlane32_swap_b32_e32 v242, v243
	v_permlane32_swap_b32_e32 v64, v66
	v_permlane32_swap_b32_e32 v65, v67
	v_permlane32_swap_b32_e32 v68, v70
	v_permlane32_swap_b32_e32 v69, v71
	v_permlane32_swap_b32_e32 v72, v74
	v_permlane32_swap_b32_e32 v73, v75
	v_permlane32_swap_b32_e32 v76, v78
	v_permlane32_swap_b32_e32 v77, v79
	s_cmp_eq_u32 s8, 0
	s_cselect_b64 s[8:9], -1, 0
	s_add_u32 s41, s18, s38
	s_addc_u32 s42, s19, s39
	s_and_b64 vcc, exec, s[8:9]
	v_mov_b64_e32 v[112:113], v[198:199]
	v_mov_b64_e32 v[114:115], v[196:197]
	v_mov_b64_e32 v[116:117], v[196:197]
	s_mov_b64 s[20:21], s[4:5]
	s_cbranch_vccnz .LBB0_124
	s_add_u32 s20, s41, 0x64c2400
	s_addc_u32 s21, s42, 0
	v_mov_b64_e32 v[112:113], v[194:195]
	v_mov_b64_e32 v[114:115], v[192:193]
	v_mov_b64_e32 v[116:117], v[190:191]
.LBB0_124:
	s_add_u32 s43, s41, 0x64c2500
	s_addc_u32 s44, s42, 0
	s_and_b64 s[22:23], exec, s[8:9]
	s_cselect_b32 s23, s66, s44
	s_cselect_b32 s22, s27, s43
	v_lshlrev_b64 v[116:117], 1, v[116:117]
	v_lshlrev_b64 v[114:115], 1, v[114:115]
	v_lshl_add_u64 v[118:119], s[22:23], 0, v[116:117]
	v_lshl_add_u64 v[120:121], s[22:23], 0, v[114:115]
	v_lshl_add_u64 v[116:117], s[20:21], 0, v[116:117]
	v_lshl_add_u64 v[114:115], s[20:21], 0, v[114:115]
	s_add_u32 s20, s18, s10
	s_addc_u32 s21, s19, s11
	s_add_u32 s43, s20, 0x28f26400
	s_addc_u32 s44, s21, 0
	v_lshlrev_b32_e32 v180, 1, v182
	s_and_b64 s[22:23], exec, s[8:9]
	v_lshl_add_u64 v[118:119], v[118:119], 0, v[180:181]
	v_lshl_add_u64 v[116:117], v[116:117], 0, v[180:181]
	v_lshl_add_u64 v[114:115], v[114:115], 0, v[180:181]
	s_cselect_b32 s22, s60, s44
	s_cselect_b32 s23, s96, s43
	v_lshl_add_u64 v[120:121], v[120:121], 0, v[180:181]
	global_load_dwordx4 v[160:163], v[118:119], off
	global_load_dwordx4 v[164:167], v[120:121], off
	global_load_dwordx4 v[168:171], v[116:117], off
	global_load_dwordx4 v[172:175], v[114:115], off
	v_mov_b32_e32 v114, s23
	v_mov_b32_e32 v115, s22
	v_lshl_add_u64 v[112:113], v[112:113], 1, v[114:115]
	v_lshlrev_b32_e32 v200, 1, v188
	v_mov_b32_e32 v201, v181
	v_lshl_add_u64 v[112:113], v[112:113], 0, v[200:201]
	global_load_dwordx4 v[176:179], v[112:113], off
	ds_read_b64_tr_b16 v[112:113], v187 offset:0
	ds_read_b64_tr_b16 v[114:115], v187 offset:0x800
	ds_read_b64_tr_b16 v[116:117], v187 offset:0x1000
	ds_read_b64_tr_b16 v[118:119], v187 offset:0x1800
	ds_read_b64_tr_b16 v[120:121], v187 offset:0x2000
	ds_read_b64_tr_b16 v[122:123], v187 offset:0x2800
	ds_read_b64_tr_b16 v[124:125], v187 offset:0x3000
	ds_read_b64_tr_b16 v[126:127], v187 offset:0x3800
	s_nop 0
	s_waitcnt lgkmcnt(4)
	v_mfma_f32_32x32x16_bf16 v[16:31], v[64:67], v[112:115], v[16:31]
	ds_read_b64_tr_b16 v[112:113], v187 offset:0x200
	ds_read_b64_tr_b16 v[114:115], v187 offset:0xa00
	v_mfma_f32_32x32x16_bf16 v[16:31], v[68:71], v[116:119], v[16:31]
	ds_read_b64_tr_b16 v[116:117], v187 offset:0x1200
	ds_read_b64_tr_b16 v[118:119], v187 offset:0x1a00
	s_waitcnt lgkmcnt(4)
	v_mfma_f32_32x32x16_bf16 v[16:31], v[72:75], v[120:123], v[16:31]
	ds_read_b64_tr_b16 v[120:121], v187 offset:0x2200
	ds_read_b64_tr_b16 v[122:123], v187 offset:0x2a00
	v_mfma_f32_32x32x16_bf16 v[16:31], v[76:79], v[124:127], v[16:31]
	ds_read_b64_tr_b16 v[124:125], v187 offset:0x3200
	ds_read_b64_tr_b16 v[126:127], v187 offset:0x3a00
	s_waitcnt lgkmcnt(4)
	v_mfma_f32_32x32x16_bf16 v[32:47], v[64:67], v[112:115], v[32:47]
	ds_read_b64_tr_b16 v[112:113], v187 offset:0x400
	ds_read_b64_tr_b16 v[114:115], v187 offset:0xc00
	v_mfma_f32_32x32x16_bf16 v[32:47], v[68:71], v[116:119], v[32:47]
	ds_read_b64_tr_b16 v[116:117], v187 offset:0x1400
	ds_read_b64_tr_b16 v[118:119], v187 offset:0x1c00
	s_waitcnt lgkmcnt(4)
	v_mfma_f32_32x32x16_bf16 v[32:47], v[72:75], v[120:123], v[32:47]
	ds_read_b64_tr_b16 v[120:121], v187 offset:0x2400
	ds_read_b64_tr_b16 v[122:123], v187 offset:0x2c00
	v_mfma_f32_32x32x16_bf16 v[32:47], v[76:79], v[124:127], v[32:47]
	ds_read_b64_tr_b16 v[124:125], v187 offset:0x3400
	ds_read_b64_tr_b16 v[126:127], v187 offset:0x3c00
	s_waitcnt lgkmcnt(4)
	v_mfma_f32_32x32x16_bf16 v[48:63], v[64:67], v[112:115], v[48:63]
	ds_read_b64_tr_b16 v[112:113], v187 offset:0x600
	ds_read_b64_tr_b16 v[114:115], v187 offset:0xe00
	v_mfma_f32_32x32x16_bf16 v[48:63], v[68:71], v[116:119], v[48:63]
	ds_read_b64_tr_b16 v[116:117], v187 offset:0x1600
	ds_read_b64_tr_b16 v[118:119], v187 offset:0x1e00
	s_waitcnt lgkmcnt(4)
	v_mfma_f32_32x32x16_bf16 v[48:63], v[72:75], v[120:123], v[48:63]
	ds_read_b64_tr_b16 v[120:121], v187 offset:0x2600
	ds_read_b64_tr_b16 v[122:123], v187 offset:0x2e00
	v_mfma_f32_32x32x16_bf16 v[48:63], v[76:79], v[124:127], v[48:63]
	ds_read_b64_tr_b16 v[124:125], v187 offset:0x3600
	ds_read_b64_tr_b16 v[126:127], v187 offset:0x3e00
	s_waitcnt lgkmcnt(4)
	v_mfma_f32_32x32x16_bf16 v[0:15], v[64:67], v[112:115], v[0:15]
	v_max_f32_e32 v64, v97, v97
	v_max_f32_e32 v65, v96, v96
	v_max_f32_e32 v64, v65, v64
	v_max3_f32 v64, v64, v98, v99
	v_max3_f32 v64, v64, v100, v101
	v_max3_f32 v64, v64, v102, v103
	v_max3_f32 v64, v64, v104, v105
	v_mfma_f32_32x32x16_bf16 v[0:15], v[68:71], v[116:119], v[0:15]
	v_max3_f32 v64, v64, v106, v107
	v_max3_f32 v64, v64, v108, v109
	v_max3_f32 v64, v64, v110, v111
	v_max3_f32 v64, v64, v80, v81
	v_max3_f32 v64, v64, v82, v83
	v_max3_f32 v64, v64, v84, v85
	v_max3_f32 v64, v64, v86, v87
	s_waitcnt lgkmcnt(0)
	v_mfma_f32_32x32x16_bf16 v[0:15], v[72:75], v[120:123], v[0:15]
	v_max3_f32 v64, v64, v88, v89
	v_max3_f32 v64, v64, v90, v91
	v_max3_f32 v64, v64, v92, v93
	v_max3_f32 v64, v64, v94, v95
	v_mov_b32_e32 v65, v64
	s_nop 1
	v_permlane32_swap_b32_e32 v64, v65
	v_mfma_f32_32x32x16_bf16 v[0:15], v[76:79], v[124:127], v[0:15]
	v_max_f32_e32 v65, v65, v65
	v_max_f32_e32 v64, v64, v64
	v_max_f32_e32 v64, v64, v65
	v_cmp_ge_f32_e32 vcc, s63, v64
	s_cmp_eq_u64 vcc, exec
	v_mov_b32_e32 v244, 1.0
	s_cbranch_scc0 .LBB0_140
.LBB0_125:
	s_barrier
	s_waitcnt vmcnt(0)
	v_add_u32_e32 v64, 0x10000, v238
	v_cmp_gt_f32_e32 vcc, 1.0, v244
	ds_write_b128 v211, v[160:163]
	ds_write_b128 v212, v[164:167]
	ds_write_b128 v213, v[168:171] offset:32768
	ds_write_b128 v214, v[172:175] offset:32768
	ds_write_b128 v64, v[176:179]
	s_cbranch_vccz .LBB0_129
	s_and_saveexec_b64 s[22:23], s[6:7]
	ds_write_b32 v236, v244 offset:128
	s_or_b64 exec, exec, s[22:23]
	s_waitcnt lgkmcnt(0)
	v_add_u32_e32 v76, s30, v186
	ds_read_b128 v[64:67], v76 offset:224
	ds_read_b128 v[68:71], v76 offset:192
	ds_read_b128 v[72:75], v76 offset:160
	ds_read_b128 v[76:79], v76 offset:128
	s_waitcnt lgkmcnt(3)
	v_pk_mul_f32 v[28:29], v[28:29], v[64:65]
	s_waitcnt lgkmcnt(2)
	v_pk_mul_f32 v[24:25], v[24:25], v[68:69]
	s_waitcnt lgkmcnt(1)
	v_pk_mul_f32 v[20:21], v[20:21], v[72:73]
	v_pk_mul_f32 v[30:31], v[30:31], v[66:67]
	v_pk_mul_f32 v[26:27], v[26:27], v[70:71]
	v_pk_mul_f32 v[22:23], v[22:23], v[74:75]
	s_waitcnt lgkmcnt(0)
	v_pk_mul_f32 v[18:19], v[18:19], v[78:79]
	v_pk_mul_f32 v[16:17], v[16:17], v[76:77]
	v_pk_mul_f32 v[44:45], v[44:45], v[64:65]
	v_pk_mul_f32 v[40:41], v[40:41], v[68:69]
	v_pk_mul_f32 v[36:37], v[36:37], v[72:73]
	v_pk_mul_f32 v[46:47], v[46:47], v[66:67]
	v_pk_mul_f32 v[42:43], v[42:43], v[70:71]
	v_pk_mul_f32 v[38:39], v[38:39], v[74:75]
	v_pk_mul_f32 v[34:35], v[34:35], v[78:79]
	v_pk_mul_f32 v[32:33], v[32:33], v[76:77]
	v_pk_mul_f32 v[60:61], v[60:61], v[64:65]
	v_pk_mul_f32 v[56:57], v[56:57], v[68:69]
	v_pk_mul_f32 v[52:53], v[52:53], v[72:73]
	v_pk_mul_f32 v[62:63], v[62:63], v[66:67]
	v_pk_mul_f32 v[58:59], v[58:59], v[70:71]
	v_pk_mul_f32 v[54:55], v[54:55], v[74:75]
	v_pk_mul_f32 v[50:51], v[50:51], v[78:79]
	v_pk_mul_f32 v[48:49], v[48:49], v[76:77]
	v_pk_mul_f32 v[12:13], v[12:13], v[64:65]
	v_pk_mul_f32 v[8:9], v[8:9], v[68:69]
	v_pk_mul_f32 v[4:5], v[4:5], v[72:73]
	v_pk_mul_f32 v[14:15], v[14:15], v[66:67]
	v_pk_mul_f32 v[10:11], v[10:11], v[70:71]
	v_pk_mul_f32 v[6:7], v[6:7], v[74:75]
	v_pk_mul_f32 v[2:3], v[2:3], v[78:79]
	v_pk_mul_f32 v[0:1], v[0:1], v[76:77]
.LBB0_129:
	v_exp_f32_e32 v73, v96
	v_exp_f32_e32 v75, v97
	v_exp_f32_e32 v76, v98
	v_exp_f32_e32 v77, v99
	v_exp_f32_e32 v78, v100
	v_exp_f32_e32 v79, v101
	v_exp_f32_e32 v72, v102
	v_exp_f32_e32 v74, v103
	v_exp_f32_e32 v66, v104
	v_exp_f32_e32 v67, v105
	v_exp_f32_e32 v68, v106
	v_exp_f32_e32 v69, v110
	v_exp_f32_e32 v71, v107
	v_exp_f32_e32 v64, v108
	v_exp_f32_e32 v65, v109
	v_exp_f32_e32 v70, v111
	s_waitcnt lgkmcnt(0)
	s_barrier
	ds_read_b128 v[246:249], v215 offset:32768
	ds_read_b128 v[250:253], v215 offset:40960
	v_xor_b32_e32 v112, 0x80000000, v235
	v_mov_b32_e32 v113, v112
	v_mov_b32_e32 v114, v112
	v_mov_b32_e32 v115, v112
	v_mov_b32_e32 v116, v112
	v_mov_b32_e32 v117, v112
	v_mov_b32_e32 v118, v112
	v_mov_b32_e32 v119, v112
	v_mov_b32_e32 v120, v112
	v_mov_b32_e32 v121, v112
	v_mov_b32_e32 v122, v112
	v_mov_b32_e32 v123, v112
	v_mov_b32_e32 v124, v112
	v_mov_b32_e32 v125, v112
	v_mov_b32_e32 v126, v112
	v_mov_b32_e32 v127, v112
	v_exp_f32_e32 v189, v80
	v_add_f32_e32 v80, 0, v73
	s_waitcnt lgkmcnt(1)
	v_mfma_f32_32x32x16_bf16 v[96:111], v[246:249], v[128:131], v[112:127]
	v_add_f32_e32 v80, v75, v80
	v_add_f32_e32 v80, v76, v80
	v_add_f32_e32 v80, v77, v80
	v_add_f32_e32 v80, v78, v80
	v_add_f32_e32 v80, v79, v80
	v_add_f32_e32 v80, v72, v80
	v_add_f32_e32 v80, v74, v80
	s_waitcnt lgkmcnt(0)
	v_mfma_f32_32x32x16_bf16 v[112:127], v[250:253], v[128:131], v[112:127]
	ds_read_b128 v[246:249], v216 offset:32768
	ds_read_b128 v[250:253], v216 offset:40960
	v_add_f32_e32 v80, v66, v80
	v_add_f32_e32 v80, v67, v80
	v_add_f32_e32 v80, v68, v80
	v_add_f32_e32 v80, v71, v80
	v_add_f32_e32 v80, v64, v80
	v_exp_f32_e32 v201, v81
	s_waitcnt lgkmcnt(1)
	v_mfma_f32_32x32x16_bf16 v[96:111], v[246:249], v[132:135], v[96:111]
	v_add_f32_e32 v80, v65, v80
	v_add_f32_e32 v80, v69, v80
	v_add_f32_e32 v80, v70, v80
	v_exp_f32_e32 v84, v84
	v_add_f32_e32 v80, v189, v80
	v_exp_f32_e32 v85, v85
	v_add_f32_e32 v80, v201, v80
	s_waitcnt lgkmcnt(0)
	v_mfma_f32_32x32x16_bf16 v[112:127], v[250:253], v[132:135], v[112:127]
	ds_read_b128 v[246:249], v217 offset:32768
	ds_read_b128 v[250:253], v217 offset:40960
	v_exp_f32_e32 v86, v86
	v_exp_f32_e32 v87, v87
	v_exp_f32_e32 v90, v90
	v_exp_f32_e32 v91, v91
	v_exp_f32_e32 v92, v92
	v_exp_f32_e32 v93, v93
	s_waitcnt lgkmcnt(1)
	v_mfma_f32_32x32x16_bf16 v[96:111], v[246:249], v[136:139], v[96:111]
	v_exp_f32_e32 v94, v94
	v_exp_f32_e32 v95, v95
	v_cvt_pk_bf16_f32 v81, v76, v77
	v_cvt_pk_bf16_f32 v66, v66, v67
	v_cvt_pk_bf16_f32 v67, v68, v71
	v_cvt_pk_bf16_f32 v68, v64, v65
	v_cvt_pk_bf16_f32 v69, v69, v70
	s_waitcnt lgkmcnt(0)
	v_mfma_f32_32x32x16_bf16 v[112:127], v[250:253], v[136:139], v[112:127]
	ds_read_b128 v[246:249], v218 offset:32768
	ds_read_b128 v[250:253], v218 offset:40960
	v_cvt_pk_bf16_f32 v77, v90, v91
	v_permlane32_swap_b32_e32 v66, v68
	v_permlane32_swap_b32_e32 v67, v69
	s_waitcnt lgkmcnt(1)
	v_mfma_f32_32x32x16_bf16 v[96:111], v[246:249], v[140:143], v[96:111]
	s_waitcnt lgkmcnt(0)
	v_mfma_f32_32x32x16_bf16 v[112:127], v[250:253], v[140:143], v[112:127]
	ds_read_b128 v[246:249], v219 offset:32768
	ds_read_b128 v[250:253], v219 offset:40960
	s_waitcnt lgkmcnt(1)
	v_mfma_f32_32x32x16_bf16 v[96:111], v[246:249], v[144:147], v[96:111]
	ds_read_b128 v[246:249], v220 offset:32768
	s_waitcnt lgkmcnt(1)
	v_mfma_f32_32x32x16_bf16 v[112:127], v[250:253], v[144:147], v[112:127]
	ds_read_b128 v[250:253], v220 offset:40960
	s_waitcnt lgkmcnt(1)
	v_mfma_f32_32x32x16_bf16 v[96:111], v[246:249], v[148:151], v[96:111]
	ds_read_b128 v[246:249], v221 offset:32768
	s_waitcnt lgkmcnt(1)
	v_mfma_f32_32x32x16_bf16 v[112:127], v[250:253], v[148:151], v[112:127]
	ds_read_b128 v[250:253], v221 offset:40960
	s_waitcnt lgkmcnt(1)
	v_mfma_f32_32x32x16_bf16 v[96:111], v[246:249], v[152:155], v[96:111]
	ds_read_b128 v[246:249], v222 offset:32768
	s_waitcnt lgkmcnt(1)
	v_mfma_f32_32x32x16_bf16 v[112:127], v[250:253], v[152:155], v[112:127]
	ds_read_b128 v[250:253], v222 offset:40960
	s_waitcnt lgkmcnt(1)
	v_mfma_f32_32x32x16_bf16 v[96:111], v[246:249], v[156:159], v[96:111]
	s_waitcnt lgkmcnt(0)
	v_mfma_f32_32x32x16_bf16 v[112:127], v[250:253], v[156:159], v[112:127]
	ds_read_b128 v[246:249], v224
	ds_read_b128 v[250:253], v224 offset:4096
	ds_read_b128 v[206:209], v225
	s_waitcnt lgkmcnt(0)
	v_mfma_f32_32x32x16_bf16 v[96:111], v[246:249], v[206:209], v[96:111]
	v_mfma_f32_32x32x16_bf16 v[112:127], v[250:253], v[206:209], v[112:127]
	ds_read_b128 v[206:209], v227
	ds_read_b128 v[246:249], v227 offset:4096
	ds_read_b128 v[250:253], v228
	s_waitcnt lgkmcnt(0)
	v_mfma_f32_32x32x16_bf16 v[96:111], v[206:209], v[250:253], v[96:111]
	v_mfma_f32_32x32x16_bf16 v[112:127], v[246:249], v[250:253], v[112:127]
	ds_read_b128 v[206:209], v230
	ds_read_b128 v[246:249], v230 offset:4096
	ds_read_b128 v[250:253], v231
	s_waitcnt lgkmcnt(0)
	v_mfma_f32_32x32x16_bf16 v[96:111], v[206:209], v[250:253], v[96:111]
	v_mfma_f32_32x32x16_bf16 v[112:127], v[246:249], v[250:253], v[112:127]
	ds_read_b128 v[206:209], v233
	ds_read_b128 v[246:249], v233 offset:4096
	ds_read_b128 v[250:253], v234
	s_waitcnt lgkmcnt(0)
	v_mfma_f32_32x32x16_bf16 v[96:111], v[206:209], v[250:253], v[96:111]
	v_exp_f32_e32 v206, v82
	v_exp_f32_e32 v207, v83
	v_exp_f32_e32 v208, v88
	v_exp_f32_e32 v209, v89
	v_add_f32_e32 v80, v206, v80
	v_add_f32_e32 v80, v207, v80
	v_add_f32_e32 v80, v84, v80
	v_add_f32_e32 v80, v85, v80
	v_add_f32_e32 v80, v86, v80
	v_add_f32_e32 v80, v87, v80
	v_add_f32_e32 v80, v208, v80
	v_add_f32_e32 v80, v209, v80
	v_mfma_f32_32x32x16_bf16 v[112:127], v[246:249], v[250:253], v[112:127]
	v_add_f32_e32 v80, v90, v80
	v_add_f32_e32 v80, v91, v80
	v_add_f32_e32 v80, v92, v80
	v_add_f32_e32 v80, v93, v80
	v_add_f32_e32 v80, v94, v80
	v_add_f32_e32 v88, v95, v80
	v_mov_b32_e32 v89, v88
	v_cvt_pk_bf16_f32 v80, v73, v75
	v_cvt_pk_bf16_f32 v82, v78, v79
	v_cvt_pk_bf16_f32 v83, v72, v74
	v_cvt_pk_bf16_f32 v72, v189, v201
	v_cvt_pk_bf16_f32 v73, v206, v207
	v_cvt_pk_bf16_f32 v74, v84, v85
	v_cvt_pk_bf16_f32 v75, v86, v87
	v_cvt_pk_bf16_f32 v76, v208, v209
	v_cvt_pk_bf16_f32 v78, v92, v93
	v_cvt_pk_bf16_f32 v79, v94, v95
	v_permlane32_swap_b32_e32 v88, v89
	v_permlane32_swap_b32_e32 v80, v82
	v_permlane32_swap_b32_e32 v81, v83
	v_permlane32_swap_b32_e32 v72, v74
	v_permlane32_swap_b32_e32 v73, v75
	v_permlane32_swap_b32_e32 v76, v78
	v_permlane32_swap_b32_e32 v77, v79
	s_add_i32 s43, s36, 1
	s_cmp_le_u32 s43, s25
	s_cselect_b64 s[22:23], -1, 0
	s_cmp_gt_u32 s43, s25
	s_cbranch_scc1 .LBB0_131
	s_add_u32 s44, s41, 0x6502400
	s_addc_u32 s45, s42, 0
	s_add_u32 s46, s41, 0x6502500
	s_addc_u32 s47, s42, 0
	v_lshlrev_b64 v[64:65], 1, v[190:191]
	v_lshl_add_u64 v[70:71], s[46:47], 0, v[64:65]
	v_lshlrev_b64 v[84:85], 1, v[192:193]
	v_lshl_add_u64 v[70:71], v[70:71], 0, v[180:181]
	v_lshl_add_u64 v[86:87], s[46:47], 0, v[84:85]
	v_lshl_add_u64 v[64:65], s[44:45], 0, v[64:65]
	v_lshl_add_u64 v[86:87], v[86:87], 0, v[180:181]
	global_load_dwordx4 v[160:163], v[70:71], off
	global_load_dwordx4 v[164:167], v[86:87], off
	v_lshl_add_u64 v[64:65], v[64:65], 0, v[180:181]
	v_lshl_add_u64 v[70:71], s[44:45], 0, v[84:85]
	v_lshl_add_u64 v[70:71], v[70:71], 0, v[180:181]
	global_load_dwordx4 v[168:171], v[64:65], off
	global_load_dwordx4 v[172:175], v[70:71], off
	v_lshl_add_u64 v[64:65], v[194:195], 1, s[20:21]
	v_mov_b32_e32 v201, v181
	v_lshl_add_u64 v[64:65], v[64:65], 0, v[200:201]
	v_add_co_u32_e32 v64, vcc, 0x28f28000, v64
	s_nop 1
	v_addc_co_u32_e32 v65, vcc, 0, v65, vcc
	global_load_dwordx4 v[176:179], v[64:65], off offset:1024
.LBB0_131:
	ds_read_b64_tr_b16 v[84:85], v240 offset:0
	ds_read_b64_tr_b16 v[86:87], v240 offset:0x800
	ds_read_b64_tr_b16 v[90:91], v240 offset:0x1000
	ds_read_b64_tr_b16 v[92:93], v240 offset:0x1800
	ds_read_b64_tr_b16 v[206:207], v240 offset:0x2000
	ds_read_b64_tr_b16 v[208:209], v240 offset:0x2800
	ds_read_b64_tr_b16 v[246:247], v240 offset:0x3000
	ds_read_b64_tr_b16 v[248:249], v240 offset:0x3800
	s_nop 0
	s_waitcnt lgkmcnt(4)
	v_mfma_f32_32x32x16_bf16 v[16:31], v[80:83], v[84:87], v[16:31]
	ds_read_b64_tr_b16 v[84:85], v240 offset:0x200
	ds_read_b64_tr_b16 v[86:87], v240 offset:0xa00
	v_mfma_f32_32x32x16_bf16 v[16:31], v[66:69], v[90:93], v[16:31]
	ds_read_b64_tr_b16 v[90:91], v240 offset:0x1200
	ds_read_b64_tr_b16 v[92:93], v240 offset:0x1a00
	s_waitcnt lgkmcnt(4)
	v_mfma_f32_32x32x16_bf16 v[16:31], v[72:75], v[206:209], v[16:31]
	ds_read_b64_tr_b16 v[206:207], v240 offset:0x2200
	ds_read_b64_tr_b16 v[208:209], v240 offset:0x2a00
	v_mfma_f32_32x32x16_bf16 v[16:31], v[76:79], v[246:249], v[16:31]
	ds_read_b64_tr_b16 v[246:247], v240 offset:0x3200
	ds_read_b64_tr_b16 v[248:249], v240 offset:0x3a00
	s_waitcnt lgkmcnt(4)
	v_mfma_f32_32x32x16_bf16 v[32:47], v[80:83], v[84:87], v[32:47]
	ds_read_b64_tr_b16 v[84:85], v240 offset:0x400
	ds_read_b64_tr_b16 v[86:87], v240 offset:0xc00
	v_mfma_f32_32x32x16_bf16 v[32:47], v[66:69], v[90:93], v[32:47]
	ds_read_b64_tr_b16 v[90:91], v240 offset:0x1400
	ds_read_b64_tr_b16 v[92:93], v240 offset:0x1c00
	s_waitcnt lgkmcnt(4)
	v_mfma_f32_32x32x16_bf16 v[32:47], v[72:75], v[206:209], v[32:47]
	ds_read_b64_tr_b16 v[206:207], v240 offset:0x2400
	ds_read_b64_tr_b16 v[208:209], v240 offset:0x2c00
	v_mfma_f32_32x32x16_bf16 v[32:47], v[76:79], v[246:249], v[32:47]
	ds_read_b64_tr_b16 v[246:247], v240 offset:0x3400
	ds_read_b64_tr_b16 v[248:249], v240 offset:0x3c00
	s_waitcnt lgkmcnt(4)
	v_mfma_f32_32x32x16_bf16 v[48:63], v[80:83], v[84:87], v[48:63]
	ds_read_b64_tr_b16 v[84:85], v240 offset:0x600
	ds_read_b64_tr_b16 v[86:87], v240 offset:0xe00
	v_mfma_f32_32x32x16_bf16 v[48:63], v[66:69], v[90:93], v[48:63]
	ds_read_b64_tr_b16 v[90:91], v240 offset:0x1600
	ds_read_b64_tr_b16 v[92:93], v240 offset:0x1e00
	s_waitcnt lgkmcnt(4)
	v_mfma_f32_32x32x16_bf16 v[48:63], v[72:75], v[206:209], v[48:63]
	ds_read_b64_tr_b16 v[206:207], v240 offset:0x2600
	ds_read_b64_tr_b16 v[208:209], v240 offset:0x2e00
	v_mfma_f32_32x32x16_bf16 v[48:63], v[76:79], v[246:249], v[48:63]
	ds_read_b64_tr_b16 v[246:247], v240 offset:0x3600
	ds_read_b64_tr_b16 v[248:249], v240 offset:0x3e00
	s_waitcnt lgkmcnt(4)
	v_mfma_f32_32x32x16_bf16 v[0:15], v[80:83], v[84:87], v[0:15]
	v_max_f32_e32 v80, v97, v97
	v_max_f32_e32 v81, v96, v96
	v_cndmask_b32_e64 v87, v105, v204, s[8:9]
	v_cndmask_b32_e64 v86, v104, v204, s[8:9]
	v_cndmask_b32_e64 v85, v107, v204, s[8:9]
	v_cndmask_b32_e64 v84, v106, v204, s[8:9]
	v_cndmask_b32_e64 v83, v109, v204, s[8:9]
	v_mfma_f32_32x32x16_bf16 v[0:15], v[66:69], v[90:93], v[0:15]
	v_max_f32_e32 v90, v81, v80
	v_max3_f32 v90, v90, v98, v99
	v_max3_f32 v90, v90, v100, v101
	v_max3_f32 v90, v90, v102, v103
	v_max3_f32 v90, v90, v86, v87
	v_cndmask_b32_e64 v82, v108, v204, s[8:9]
	v_max3_f32 v90, v90, v84, v85
	s_waitcnt lgkmcnt(0)
	v_mfma_f32_32x32x16_bf16 v[0:15], v[72:75], v[206:209], v[0:15]
	v_cndmask_b32_e64 v81, v111, v204, s[8:9]
	v_cndmask_b32_e64 v80, v110, v204, s[8:9]
	v_max3_f32 v90, v90, v82, v83
	v_max3_f32 v90, v90, v80, v81
	v_cndmask_b32_e64 v75, v117, v204, s[8:9]
	v_cndmask_b32_e64 v74, v116, v204, s[8:9]
	v_cndmask_b32_e64 v73, v119, v204, s[8:9]
	v_mfma_f32_32x32x16_bf16 v[0:15], v[76:79], v[246:249], v[0:15]
	v_cndmask_b32_e64 v79, v113, v204, s[8:9]
	v_cndmask_b32_e64 v78, v112, v204, s[8:9]
	v_cndmask_b32_e64 v77, v115, v204, s[8:9]
	v_cndmask_b32_e64 v76, v114, v204, s[8:9]
	v_max3_f32 v90, v90, v78, v79
	v_max3_f32 v90, v90, v76, v77
	v_cndmask_b32_e64 v72, v118, v204, s[8:9]
	v_max3_f32 v90, v90, v74, v75
	v_cndmask_b32_e64 v71, v121, v204, s[8:9]
	v_cndmask_b32_e64 v70, v120, v204, s[8:9]
	v_max3_f32 v90, v90, v72, v73
	v_cndmask_b32_e64 v69, v123, v204, s[8:9]
	v_cndmask_b32_e64 v68, v122, v204, s[8:9]
	v_max3_f32 v90, v90, v70, v71
	v_cndmask_b32_e64 v67, v125, v204, s[8:9]
	v_cndmask_b32_e64 v66, v124, v204, s[8:9]
	v_max3_f32 v90, v90, v68, v69
	v_cndmask_b32_e64 v65, v127, v204, s[8:9]
	v_cndmask_b32_e64 v64, v126, v204, s[8:9]
	v_max3_f32 v90, v90, v66, v67
	v_max3_f32 v90, v90, v64, v65
	v_mov_b32_e32 v91, v90
	s_nop 1
	v_permlane32_swap_b32_e32 v90, v91
	v_max_f32_e32 v91, v91, v91
	v_max_f32_e32 v90, v90, v90
	v_max_f32_e32 v91, v90, v91
	v_cmp_ge_f32_e32 vcc, s63, v91
	s_cmp_eq_u64 vcc, exec
	v_mov_b32_e32 v90, 1.0
	s_cbranch_scc0 .LBB0_141
.LBB0_132:
	s_barrier
	s_waitcnt vmcnt(0)
	s_andn2_b64 vcc, exec, s[22:23]
	s_cbranch_vccnz .LBB0_134
	ds_write_b128 v211, v[160:163] offset:16384
	ds_write_b128 v212, v[164:167] offset:16384
	ds_write_b128 v213, v[168:171] offset:49152
	ds_write_b128 v214, v[172:175] offset:49152
	ds_write_b128 v239, v[176:179]
